# rwkv scan consumer remapped: lane = 2 state rows x 4 columns (16 column groups per DPP row): half the LDS operand traffic, two independent dependency chains per wave, 16-lane reduce-scatter every 16 s
# speedup vs baseline: 1.0298x; 1.0228x over previous
; DEV void scan_tile(const Params& p, int l, int tile, char* smem) {
;   const int half = tile & 1, dir = (tile >> 1) & 1, h = (tile >> 2) & 7, b = tile >> 5;
;   float* arr = (float*)smem;
;   float* ybuf = arr + 2 * 32 * 384;
;   const bf16_t* ZRS = (const bf16_t*)(p.ws + O_ZRS);
;   const bf16_t* E = (const bf16_t*)(p.ws + (dir ? O_EB : O_EF));
;   const bf16_t* Aa = (const bf16_t*)(p.ws + (dir ? O_AB : O_AF));
;   bf16_t* YS = (bf16_t*)(p.ws + (dir ? O_YSB : O_YSF));
;   const int tid = ltid(), lane = tid & 63;
;   const int w = __builtin_amdgcn_readfirstlane(tid >> 6);
;   const int col = h * 64 + lane;
;   const float kkp = p.rwkv_kk[l * 512 + col], kap = p.rwkv_ka[l * 512 + col];
;   auto produce = [&](int ch, int buf, int pw, int npw) {
; #pragma unroll
;     for (int i0 = 0; i0 < 32; i0 += 4 * npw) {
;       bf16_t rr[4], rk[4], rv[4], re[4], ra[4];
; #pragma unroll
;       for (int i = 0; i < 4; ++i) {
;         const int R = scan_row(ch * 32 + i0 + pw + npw * i, dir, b);
;         rr[i] = ZRS[(size_t)R * 1536 + col];
;         rk[i] = ZRS[(size_t)R * 1536 + 512 + col];
;         rv[i] = ZRS[(size_t)R * 1536 + 1024 + col];
;         re[i] = E[(size_t)R * 512 + col];
;         ra[i] = Aa[(size_t)R * 512 + col];
;       }
; #pragma unroll
;       for (int i = 0; i < 4; ++i) {
;         const int sl = i0 + pw + npw * i;
;         const float r = bf2f(rr[i]), k = bf2f(rk[i]), v = bf2f(rv[i]), e = bf2f(re[i]), a = bf2f(ra[i]);
;         const float kkv = k * kkp;
;         const float inv = __builtin_amdgcn_rsqf(fmaxf(wsum(kkv * kkv), 1e-24f));
;         const float kk = kkv * inv;
;         float* d = arr + (buf * 32 + sl) * 384 + lane;
;         d[0] = -kk;
;         d[64] = __expf(-e);
;         d[128] = kk * a;
;         d[192] = k * (1.f + (a - 1.f) * kap);
;         d[256] = r;
;         d[320] = v;
;       }
;     }
;   };
;   auto flush = [&](int ch, int buf, int t256) {
; #pragma unroll
;     for (int q = 0; q < 2; ++q) {
;       const int idx = t256 + 256 * q, sl = idx >> 4, rp = (idx & 15) * 2;
;       const int R = scan_row(ch * 32 + sl, dir, b);
;       const float* yb = ybuf + buf * 1024 + sl * 32 + rp;
;       *(unsigned*)(YS + (size_t)R * 512 + h * 64 + half * 32 + rp) = pk2(yb[0], yb[1]);
;     }
;   };
;   __syncthreads();
;   produce(0, 0, w, 8);
;   __syncthreads();
;   f32x4 S0 = {0.f, 0.f, 0.f, 0.f}, S1 = {0.f, 0.f, 0.f, 0.f};
.LBB0_193:
	s_and_b32 s30, s94, 1
	s_bfe_u32 s31, s94, 0x10001
	s_bfe_u32 s36, s94, 0x30002
	s_lshr_b32 s37, s94, 5
	v_readfirstlane_b32 s47, v226
	s_lshl_b32 s58, s36, 7
	s_add_u32 s38, s74, 0xee00000
	s_addc_u32 s39, s75, 0
	s_add_u32 s38, s38, s58
	s_addc_u32 s39, s39, 0
	s_lshr_b32 s47, s47, 6
	s_cmp_eq_u32 s31, 0
	s_cselect_b32 s59, 0, 0x6600000
	s_add_u32 s40, s74, s59
	s_addc_u32 s41, s75, 0
	s_add_u32 s40, s40, s58
	s_addc_u32 s41, s41, 0
	s_mov_b32 s59, 0xaa00000
	s_cmp_eq_u32 s31, 0
	s_cselect_b32 s59, 0x8800000, s59
	s_add_u32 s42, s74, s59
	s_addc_u32 s43, s75, 0
	s_add_u32 s42, s42, s58
	s_addc_u32 s43, s43, 0
	s_mov_b32 s59, 0x15400000
	s_cmp_eq_u32 s31, 0
	s_cselect_b32 s59, 0xcc00000, s59
	s_add_u32 s44, s74, s59
	s_addc_u32 s45, s75, 0
	s_lshl_b32 s59, s30, 6
	s_add_u32 s58, s58, s59
	s_add_u32 s44, s44, s58
	s_addc_u32 s45, s45, 0
	s_mov_b32 s46, 0
	v_and_b32_e32 v120, 63, v226
	v_and_b32_e32 v121, 7, v120
	v_lshrrev_b32_e32 v122, 3, v120
	s_cmp_lt_u32 s47, 4
	s_cbranch_scc1 .Lsc_consumer
	s_sub_u32 s58, s47, 4
	s_lshl_b32 s58, s58, 3
	v_add_u32_e32 v123, s58, v122
	v_sub_u32_e32 v32, 31, v123
	s_cmp_eq_u32 s31, 0
	s_cselect_b64 vcc, -1, 0
	v_cndmask_b32_e32 v32, v32, v123, vcc
	v_lshlrev_b32_e32 v33, 4, v121
	v_mul_u32_u24_e32 v20, 0xc00, v32
	v_add_u32_e32 v20, v20, v33
	v_lshl_add_u32 v21, v32, 10, v33
	v_mul_u32_u24_e32 v22, 0x600, v123
	v_lshl_add_u32 v22, v121, 5, v22
	v_lshlrev_b32_e32 v23, 7, v123
	v_lshl_add_u32 v23, v121, 4, v23
	v_add_u32_e32 v23, 0x18000, v23
	v_lshlrev_b32_e32 v24, 10, v32
	v_lshl_add_u32 v24, v121, 3, v24
	s_lshl_b32 s58, s36, 6
	s_add_u32 s58, s58, s79
	v_lshl_add_u32 v34, v121, 3, s58
	v_lshlrev_b32_e32 v34, 2, v34
	global_load_dwordx4 v[40:43], v34, s[8:9]
	global_load_dwordx4 v[44:47], v34, s[8:9] offset:16
	global_load_dwordx4 v[48:51], v34, s[10:11]
	global_load_dwordx4 v[52:55], v34, s[10:11] offset:16
	v_mov_b32_e32 v98, 0xbfb8aa3b
	v_mov_b32_e32 v99, 0xbfb8aa3b
	v_mov_b32_e32 v124, -1.0
	v_mov_b32_e32 v125, -1.0
	v_mov_b32_e32 v126, 1.0
	v_mov_b32_e32 v127, 1.0
	s_mov_b32 s54, 0xc000
	s_mov_b32 s66, 0x18000
	s_mov_b32 s67, 0
	s_mov_b32 s68, 0x8000
	s_mov_b32 s69, 0
	s_cmp_eq_u32 s31, 0
	s_cbranch_scc1 .Lsc_dpos
	s_sub_u32 s66, 0, s66
	s_mov_b32 s67, -1
	s_sub_u32 s68, 0, s68
	s_mov_b32 s69, -1
.Lsc_dpos:
	s_sub_u32 s60, s46, 8
	s_cmp_lt_u32 s46, 8
	s_cselect_b32 s60, s46, s60
	s_lshl_b32 s60, s60, 5
	s_lshl_b32 s61, s37, 8
	s_add_u32 s61, s61, 0x8000
	s_lshl_b32 s59, s37, 12
	s_cmp_lt_u32 s46, 8
	s_cselect_b32 s59, s61, s59
	s_movk_i32 s61, 0xfe0
	s_cselect_b32 s61, 0xe0, s61
	s_sub_u32 s61, s61, s60
	s_cmp_eq_u32 s31, 0
	s_cselect_b32 s60, s60, s61
	s_add_u32 s59, s59, s60
	s_mul_i32 s60, s59, 0xc00
	s_add_u32 s48, s38, s60
	s_addc_u32 s49, s39, 0
	s_lshl_b32 s60, s59, 10
	s_add_u32 s50, s40, s60
	s_addc_u32 s51, s41, 0
	s_add_u32 s52, s42, s60
	s_addc_u32 s53, s43, 0
	global_load_dwordx4 v[0:3], v20, s[48:49]
	global_load_dwordx4 v[4:7], v20, s[48:49] offset:1024
	global_load_dwordx4 v[8:11], v20, s[48:49] offset:2048
	global_load_dwordx4 v[12:15], v21, s[50:51]
	global_load_dwordx4 v[16:19], v21, s[52:53]
	s_barrier
	s_waitcnt vmcnt(0)
	v_lshlrev_b32_e32 v56, 16, v4
	v_and_b32_e32 v57, 0xffff0000, v4
	v_lshlrev_b32_e32 v58, 16, v5
	v_and_b32_e32 v59, 0xffff0000, v5
	v_lshlrev_b32_e32 v60, 16, v6
	v_and_b32_e32 v61, 0xffff0000, v6
	v_lshlrev_b32_e32 v62, 16, v7
	v_and_b32_e32 v63, 0xffff0000, v7
	v_lshlrev_b32_e32 v64, 16, v16
	v_and_b32_e32 v65, 0xffff0000, v16
	v_lshlrev_b32_e32 v66, 16, v17
	v_and_b32_e32 v67, 0xffff0000, v17
	v_lshlrev_b32_e32 v68, 16, v18
	v_and_b32_e32 v69, 0xffff0000, v18
	v_lshlrev_b32_e32 v70, 16, v19
	v_and_b32_e32 v71, 0xffff0000, v19
	v_lshlrev_b32_e32 v72, 16, v12
	v_and_b32_e32 v73, 0xffff0000, v12
	v_lshlrev_b32_e32 v74, 16, v13
	v_and_b32_e32 v75, 0xffff0000, v13
	v_lshlrev_b32_e32 v76, 16, v14
	v_and_b32_e32 v77, 0xffff0000, v14
	v_lshlrev_b32_e32 v78, 16, v15
	v_and_b32_e32 v79, 0xffff0000, v15
	v_lshlrev_b32_e32 v80, 16, v0
	v_and_b32_e32 v81, 0xffff0000, v0
	v_lshlrev_b32_e32 v82, 16, v1
	v_and_b32_e32 v83, 0xffff0000, v1
	v_lshlrev_b32_e32 v84, 16, v2
	v_and_b32_e32 v85, 0xffff0000, v2
	v_lshlrev_b32_e32 v86, 16, v3
	v_and_b32_e32 v87, 0xffff0000, v3
	v_lshlrev_b32_e32 v88, 16, v8
	v_and_b32_e32 v89, 0xffff0000, v8
	v_lshlrev_b32_e32 v90, 16, v9
	v_and_b32_e32 v91, 0xffff0000, v9
	v_lshlrev_b32_e32 v92, 16, v10
	v_and_b32_e32 v93, 0xffff0000, v10
	v_lshlrev_b32_e32 v94, 16, v11
	v_and_b32_e32 v95, 0xffff0000, v11
	s_mov_b32 s76, 1
	s_cmp_eq_u32 s76, 8
	s_cbranch_scc1 .Lsc_lbf1
	s_add_u32 s48, s48, s66
	s_addc_u32 s49, s49, s67
	s_add_u32 s50, s50, s68
	s_addc_u32 s51, s51, s69
	s_add_u32 s52, s52, s68
	s_addc_u32 s53, s53, s69
	s_branch .Lsc_lbd1
.Lsc_lbf1:
	s_sub_u32 s60, s76, 8
	s_cmp_lt_u32 s76, 8
	s_cselect_b32 s60, s76, s60
	s_lshl_b32 s60, s60, 5
	s_lshl_b32 s61, s37, 8
	s_add_u32 s61, s61, 0x8000
	s_lshl_b32 s59, s37, 12
	s_cmp_lt_u32 s76, 8
	s_cselect_b32 s59, s61, s59
	s_movk_i32 s61, 0xfe0
	s_cselect_b32 s61, 0xe0, s61
	s_sub_u32 s61, s61, s60
	s_cmp_eq_u32 s31, 0
	s_cselect_b32 s60, s60, s61
	s_add_u32 s59, s59, s60
	s_mul_i32 s60, s59, 0xc00
	s_add_u32 s48, s38, s60
	s_addc_u32 s49, s39, 0
	s_lshl_b32 s60, s59, 10
	s_add_u32 s50, s40, s60
	s_addc_u32 s51, s41, 0
	s_add_u32 s52, s42, s60
	s_addc_u32 s53, s43, 0
; DEV void scan_tile(const Params& p, int l, int tile, char* smem) {
;     ...
;   auto produce = [&](int ch, int buf, int pw, int npw) {
; #pragma unroll
;     for (int i0 = 0; i0 < 32; i0 += 4 * npw) {
;       bf16_t rr[4], rk[4], rv[4], re[4], ra[4];
; #pragma unroll
;       for (int i = 0; i < 4; ++i) {
;         const int R = scan_row(ch * 32 + i0 + pw + npw * i, dir, b);
;         rr[i] = ZRS[(size_t)R * 1536 + col];
;         rk[i] = ZRS[(size_t)R * 1536 + 512 + col];
;         rv[i] = ZRS[(size_t)R * 1536 + 1024 + col];
;         re[i] = E[(size_t)R * 512 + col];
;         ra[i] = Aa[(size_t)R * 512 + col];
;       }
; #pragma unroll
;       for (int i = 0; i < 4; ++i) {
;         const int sl = i0 + pw + npw * i;
;         const float r = bf2f(rr[i]), k = bf2f(rk[i]), v = bf2f(rv[i]), e = bf2f(re[i]), a = bf2f(ra[i]);
;         const float kkv = k * kkp;
;         const float inv = __builtin_amdgcn_rsqf(fmaxf(wsum(kkv * kkv), 1e-24f));
;         const float kk = kkv * inv;
;         float* d = arr + (buf * 32 + sl) * 384 + lane;
;         d[0] = -kk;
;         d[64] = __expf(-e);
;         d[128] = kk * a;
;         d[192] = k * (1.f + (a - 1.f) * kap);
;         d[256] = r;
;         d[320] = v;
;       }
;     }
;     ...
;   for (int ch = 0; ch < 136; ++ch) {
;     const int buf = ch & 1;
;     if (w < 4) {
;       const float* cb = arr + buf * 32 * 384;
;       const int vo = 320 + half * 32 + w * 8 + r8;
;       float* yw = ybuf + buf * 1024 + cg * 32 + w * 8 + r8;
;       auto ldops = [&](ScanOps& o, int sl) {
;         const f32x4* b4 = (const f32x4*)(cb + sl * 384);
;         o.nkk0 = b4[cg * 2]; o.nkk1 = b4[cg * 2 + 1];
;         o.w0 = b4[16 + cg * 2]; o.w1 = b4[16 + cg * 2 + 1];
;         o.kka0 = b4[32 + cg * 2]; o.kka1 = b4[32 + cg * 2 + 1];
;         o.kd0 = b4[48 + cg * 2]; o.kd1 = b4[48 + cg * 2 + 1];
;         o.r0 = b4[64 + cg * 2]; o.r1 = b4[64 + cg * 2 + 1];
;         o.v = cb[sl * 384 + vo];
;       };
;       float ykeep = 0.f;
;       auto step = [&](const ScanOps& o, int sl) {
;         const f32x4 sA = S0 * o.nkk0 + S1 * o.nkk1;
;         const float sa = red8((sA[0] + sA[1]) + (sA[2] + sA[3]));
;         S0 = S0 * o.w0 + (o.kka0 * sa + o.kd0 * o.v);
;         S1 = S1 * o.w1 + (o.kka1 * sa + o.kd1 * o.v);
;         const f32x4 yA = S0 * o.r0 + S1 * o.r1;
;         const float y = red8((yA[0] + yA[1]) + (yA[2] + yA[3]));
.Lsc_lbd1:
	global_load_dwordx4 v[0:3], v20, s[48:49]
	global_load_dwordx4 v[4:7], v20, s[48:49] offset:1024
	global_load_dwordx4 v[8:11], v20, s[48:49] offset:2048
	global_load_dwordx4 v[12:15], v21, s[50:51]
	global_load_dwordx4 v[16:19], v21, s[52:53]
	v_pk_mul_f32 v[100:101], v[56:57], v[40:41]
	v_pk_mul_f32 v[102:103], v[58:59], v[42:43]
	v_pk_mul_f32 v[104:105], v[60:61], v[44:45]
	v_pk_mul_f32 v[106:107], v[62:63], v[46:47]
	v_pk_mul_f32 v[72:73], v[72:73], v[98:99]
	v_pk_mul_f32 v[74:75], v[74:75], v[98:99]
	v_pk_mul_f32 v[76:77], v[76:77], v[98:99]
	v_pk_mul_f32 v[78:79], v[78:79], v[98:99]
	v_pk_mul_f32 v[32:33], v[100:101], v[100:101]
	v_pk_fma_f32 v[32:33], v[102:103], v[102:103], v[32:33]
	v_pk_fma_f32 v[32:33], v[104:105], v[104:105], v[32:33]
	v_pk_fma_f32 v[32:33], v[106:107], v[106:107], v[32:33]
	v_add_f32_e32 v25, v32, v33
	v_pk_add_f32 v[116:117], v[64:65], v[124:125]
	v_pk_add_f32 v[118:119], v[66:67], v[124:125]
	v_add_f32_dpp v25, v25, v25 quad_perm:[1,0,3,2] row_mask:0xf bank_mask:0xf bound_ctrl:1
	v_pk_add_f32 v[120:121], v[68:69], v[124:125]
	v_pk_add_f32 v[122:123], v[70:71], v[124:125]
	v_add_f32_dpp v25, v25, v25 quad_perm:[2,3,0,1] row_mask:0xf bank_mask:0xf bound_ctrl:1
	v_exp_f32_e32 v72, v72
	v_exp_f32_e32 v73, v73
	v_add_f32_dpp v25, v25, v25 row_half_mirror row_mask:0xf bank_mask:0xf bound_ctrl:1
	v_exp_f32_e32 v74, v74
	v_exp_f32_e32 v75, v75
	v_exp_f32_e32 v76, v76
	v_exp_f32_e32 v77, v77
	v_exp_f32_e32 v78, v78
	v_exp_f32_e32 v79, v79
	v_max_f32_e32 v25, 0x179abe15, v25
	v_rsq_f32_e32 v25, v25
	v_pk_fma_f32 v[116:117], v[48:49], v[116:117], v[126:127]
	v_pk_fma_f32 v[118:119], v[50:51], v[118:119], v[126:127]
	v_pk_fma_f32 v[120:121], v[52:53], v[120:121], v[126:127]
	v_pk_fma_f32 v[122:123], v[54:55], v[122:123], v[126:127]
	v_sub_f32_e32 v26, 0, v25
	v_pk_mul_f32 v[116:117], v[116:117], v[56:57]
	v_pk_mul_f32 v[118:119], v[118:119], v[58:59]
	v_pk_mul_f32 v[120:121], v[120:121], v[60:61]
	v_pk_mul_f32 v[122:123], v[122:123], v[62:63]
	ds_write_b128 v22, v[72:75] offset:256
	ds_write_b128 v22, v[76:79] offset:272
	ds_write_b128 v22, v[80:83] offset:1024
	ds_write_b128 v22, v[84:87] offset:1040
	v_pk_mul_f32 v[100:101], v[100:101], v[26:27] op_sel_hi:[1,0]
	v_pk_mul_f32 v[102:103], v[102:103], v[26:27] op_sel_hi:[1,0]
	v_pk_mul_f32 v[104:105], v[104:105], v[26:27] op_sel_hi:[1,0]
	v_pk_mul_f32 v[106:107], v[106:107], v[26:27] op_sel_hi:[1,0]
	ds_write_b128 v22, v[88:91] offset:1280
	ds_write_b128 v22, v[92:95] offset:1296
	ds_write_b128 v22, v[116:119] offset:768
	ds_write_b128 v22, v[120:123] offset:784
	v_pk_mul_f32 v[108:109], v[100:101], v[64:65] neg_lo:[1,0] neg_hi:[1,0]
	v_pk_mul_f32 v[110:111], v[102:103], v[66:67] neg_lo:[1,0] neg_hi:[1,0]
	v_pk_mul_f32 v[112:113], v[104:105], v[68:69] neg_lo:[1,0] neg_hi:[1,0]
	v_pk_mul_f32 v[114:115], v[106:107], v[70:71] neg_lo:[1,0] neg_hi:[1,0]
	ds_write_b128 v22, v[100:103]
	ds_write_b128 v22, v[104:107] offset:16
	ds_write_b128 v22, v[108:111] offset:512
	ds_write_b128 v22, v[112:115] offset:528
	v_add_u32_e32 v22, s54, v22
	s_sub_u32 s54, 0, s54
	s_waitcnt lgkmcnt(0)
	s_barrier
.Lsc_ploop:
	s_cmp_ge_u32 s46, 135
	s_cbranch_scc1 .Lsc_pskip
	s_waitcnt vmcnt(0)
	v_lshlrev_b32_e32 v56, 16, v4
	v_and_b32_e32 v57, 0xffff0000, v4
	v_lshlrev_b32_e32 v58, 16, v5
	v_and_b32_e32 v59, 0xffff0000, v5
	v_lshlrev_b32_e32 v60, 16, v6
	v_and_b32_e32 v61, 0xffff0000, v6
	v_lshlrev_b32_e32 v62, 16, v7
	v_and_b32_e32 v63, 0xffff0000, v7
	v_lshlrev_b32_e32 v64, 16, v16
	v_and_b32_e32 v65, 0xffff0000, v16
	v_lshlrev_b32_e32 v66, 16, v17
	v_and_b32_e32 v67, 0xffff0000, v17
	v_lshlrev_b32_e32 v68, 16, v18
	v_and_b32_e32 v69, 0xffff0000, v18
	v_lshlrev_b32_e32 v70, 16, v19
	v_and_b32_e32 v71, 0xffff0000, v19
	v_lshlrev_b32_e32 v72, 16, v12
	v_and_b32_e32 v73, 0xffff0000, v12
	v_lshlrev_b32_e32 v74, 16, v13
	v_and_b32_e32 v75, 0xffff0000, v13
	v_lshlrev_b32_e32 v76, 16, v14
	v_and_b32_e32 v77, 0xffff0000, v14
	v_lshlrev_b32_e32 v78, 16, v15
	v_and_b32_e32 v79, 0xffff0000, v15
	v_lshlrev_b32_e32 v80, 16, v0
	v_and_b32_e32 v81, 0xffff0000, v0
	v_lshlrev_b32_e32 v82, 16, v1
	v_and_b32_e32 v83, 0xffff0000, v1
	v_lshlrev_b32_e32 v84, 16, v2
	v_and_b32_e32 v85, 0xffff0000, v2
	v_lshlrev_b32_e32 v86, 16, v3
	v_and_b32_e32 v87, 0xffff0000, v3
	v_lshlrev_b32_e32 v88, 16, v8
	v_and_b32_e32 v89, 0xffff0000, v8
	v_lshlrev_b32_e32 v90, 16, v9
	v_and_b32_e32 v91, 0xffff0000, v9
	v_lshlrev_b32_e32 v92, 16, v10
	v_and_b32_e32 v93, 0xffff0000, v10
	v_lshlrev_b32_e32 v94, 16, v11
	v_and_b32_e32 v95, 0xffff0000, v11
	s_cmp_ge_u32 s46, 134
	s_cbranch_scc1 .Lsc_pnoload
	s_add_u32 s76, s46, 2
	s_cmp_eq_u32 s76, 8
	s_cbranch_scc1 .Lsc_lbf2
	s_add_u32 s48, s48, s66
	s_addc_u32 s49, s49, s67
	s_add_u32 s50, s50, s68
	s_addc_u32 s51, s51, s69
	s_add_u32 s52, s52, s68
	s_addc_u32 s53, s53, s69
	s_branch .Lsc_lbd2

; DEV void scan_tile(const Params& p, int l, int tile, char* smem) {
;     ...
;       for (int i = 0; i < 4; ++i) {
;         const int R = scan_row(ch * 32 + i0 + pw + npw * i, dir, b);
;         rr[i] = ZRS[(size_t)R * 1536 + col];
;         rk[i] = ZRS[(size_t)R * 1536 + 512 + col];
;         rv[i] = ZRS[(size_t)R * 1536 + 1024 + col];
;         re[i] = E[(size_t)R * 512 + col];
;         ra[i] = Aa[(size_t)R * 512 + col];
;       }
.Lsc_lbd2:
	global_load_dwordx4 v[0:3], v20, s[48:49]
	global_load_dwordx4 v[4:7], v20, s[48:49] offset:1024
	global_load_dwordx4 v[8:11], v20, s[48:49] offset:2048
	global_load_dwordx4 v[12:15], v21, s[50:51]
	global_load_dwordx4 v[16:19], v21, s[52:53]

; DEV int scan_row(int step, int dir, int b) {
;   if (step < CTXL) { const int t = dir ? (CTXL - 1 - step) : step; return T_LAT + b * CTXL + t; }
;   const int s2 = step - CTXL;
;   const int t = dir ? (SEQ - 1 - s2) : s2;
;   return b * SEQ + t;
; DEV void scan_tile(const Params& p, int l, int tile, char* smem) {
;     ...
;   auto flush = [&](int ch, int buf, int t256) {
; #pragma unroll
;     for (int q = 0; q < 2; ++q) {
;       const int idx = t256 + 256 * q, sl = idx >> 4, rp = (idx & 15) * 2;
;       const int R = scan_row(ch * 32 + sl, dir, b);
;       const float* yb = ybuf + buf * 1024 + sl * 32 + rp;
;       *(unsigned*)(YS + (size_t)R * 512 + h * 64 + half * 32 + rp) = pk2(yb[0], yb[1]);
;     }
;   };
.Lsc_pskip:
	s_cmp_eq_u32 s46, 0
	s_cbranch_scc1 .Lsc_pnoflush
	s_sub_u32 s76, s46, 1
	s_cmp_eq_u32 s76, 0
	s_cbranch_scc1 .Lsc_fb0
	s_cmp_eq_u32 s76, 8
	s_cbranch_scc1 .Lsc_fbf3
	s_add_u32 s56, s56, s68
	s_addc_u32 s57, s57, s69
	s_branch .Lsc_fbd3
.Lsc_fbf3:
	s_sub_u32 s60, s76, 8
	s_cmp_lt_u32 s76, 8
	s_cselect_b32 s60, s76, s60
	s_lshl_b32 s60, s60, 5
	s_lshl_b32 s61, s37, 8
	s_add_u32 s61, s61, 0x8000
	s_lshl_b32 s59, s37, 12
	s_cmp_lt_u32 s76, 8
	s_cselect_b32 s59, s61, s59
	s_movk_i32 s61, 0xfe0
	s_cselect_b32 s61, 0xe0, s61
	s_sub_u32 s61, s61, s60
	s_cmp_eq_u32 s31, 0
	s_cselect_b32 s60, s60, s61
	s_add_u32 s59, s59, s60
	s_lshl_b32 s60, s59, 10
	s_add_u32 s56, s44, s60
	s_addc_u32 s57, s45, 0

; DEV void scan_tile(const Params& p, int l, int tile, char* smem) {
;     ...
;   auto flush = [&](int ch, int buf, int t256) {
; #pragma unroll
;     for (int q = 0; q < 2; ++q) {
;       const int idx = t256 + 256 * q, sl = idx >> 4, rp = (idx & 15) * 2;
;       const int R = scan_row(ch * 32 + sl, dir, b);
;       const float* yb = ybuf + buf * 1024 + sl * 32 + rp;
;       *(unsigned*)(YS + (size_t)R * 512 + h * 64 + half * 32 + rp) = pk2(yb[0], yb[1]);
;     }
;   };
;     ...
;       if (ch > 0) flush(ch - 1, buf ^ 1, tid - 256);
;       if (ch + 1 < 136) produce(ch + 1, buf ^ 1, pw, 4);
;     }
;     __syncthreads();
;   }
;   if (w >= 4) flush(135, 1, tid - 256);
.Lsc_fb1:
	ds_read_b128 v[28:31], v23
	s_waitcnt lgkmcnt(0)
	v_cvt_pk_bf16_f32 v28, v28, v29
	v_cvt_pk_bf16_f32 v29, v30, v31
	global_store_dwordx2 v24, v[28:29], s[56:57]
	v_xor_b32_e32 v23, 0x1000, v23
.Lsc_pnoflush:
	s_add_u32 s46, s46, 1
	s_cmp_lt_u32 s46, 136
	s_waitcnt lgkmcnt(0)
	s_barrier
	s_cbranch_scc1 .Lsc_ploop
	s_mov_b32 s76, 135
	s_cmp_eq_u32 s76, 8
	s_cbranch_scc1 .Lsc_fbf4
	s_add_u32 s56, s56, s68
	s_addc_u32 s57, s57, s69
	s_branch .Lsc_fbd4

; DEV void scan_tile(const Params& p, int l, int tile, char* smem) {
;     ...
;   };
;   __syncthreads();
;   produce(0, 0, w, 8);
;   __syncthreads();
;   f32x4 S0 = {0.f, 0.f, 0.f, 0.f}, S1 = {0.f, 0.f, 0.f, 0.f};
;   const int r8 = lane >> 3, cg = lane & 7;
;   for (int ch = 0; ch < 136; ++ch) {
;     const int buf = ch & 1;
;     if (w < 4) {
;       const float* cb = arr + buf * 32 * 384;
;       const int vo = 320 + half * 32 + w * 8 + r8;
;       float* yw = ybuf + buf * 1024 + cg * 32 + w * 8 + r8;
;       auto ldops = [&](ScanOps& o, int sl) {
;         const f32x4* b4 = (const f32x4*)(cb + sl * 384);
;         o.nkk0 = b4[cg * 2]; o.nkk1 = b4[cg * 2 + 1];
;         o.w0 = b4[16 + cg * 2]; o.w1 = b4[16 + cg * 2 + 1];
;         o.kka0 = b4[32 + cg * 2]; o.kka1 = b4[32 + cg * 2 + 1];
;         o.kd0 = b4[48 + cg * 2]; o.kd1 = b4[48 + cg * 2 + 1];
;         o.r0 = b4[64 + cg * 2]; o.r1 = b4[64 + cg * 2 + 1];
;         o.v = cb[sl * 384 + vo];
;       };
;       float ykeep = 0.f;
;       auto step = [&](const ScanOps& o, int sl) {
;         const f32x4 sA = S0 * o.nkk0 + S1 * o.nkk1;
;         const float sa = red8((sA[0] + sA[1]) + (sA[2] + sA[3]));
;         S0 = S0 * o.w0 + (o.kka0 * sa + o.kd0 * o.v);
;         S1 = S1 * o.w1 + (o.kka1 * sa + o.kd1 * o.v);
;         const f32x4 yA = S0 * o.r0 + S1 * o.r1;
;         const float y = red8((yA[0] + yA[1]) + (yA[2] + yA[3]));
;         ykeep = (cg == (sl & 7)) ? y : ykeep;
;       };
;       ScanOps oa, ob;
;       ldops(oa, 0);
; #pragma unroll
;       for (int s8 = 0; s8 < 32; s8 += 8) {
; #pragma unroll
;         for (int q = 0; q < 8; q += 2) {
;           ldops(ob, s8 + q + 1);
;           step(oa, s8 + q);
;           ldops(oa, (s8 + q + 2) & 31);
;           step(ob, s8 + q + 1);
;         }
.Lsc_fbd4:
	ds_read_b128 v[28:31], v23
	s_waitcnt lgkmcnt(0)
	v_cvt_pk_bf16_f32 v28, v28, v29
	v_cvt_pk_bf16_f32 v29, v30, v31
	global_store_dwordx2 v24, v[28:29], s[56:57]
	v_xor_b32_e32 v23, 0x1000, v23
	s_branch .LBB0_192
.Lsc_consumer:
	v_and_b32_e32 v121, 15, v120
	v_lshrrev_b32_e32 v122, 4, v120
	s_lshl_b32 s58, s47, 3
	v_add_u32_e32 v122, s58, v122
	v_lshlrev_b32_e32 v78, 4, v121
	s_lshl_b32 s58, s30, 7
	v_lshl_add_u32 v79, v122, 2, s58
	v_add_u32_e32 v81, 16, v79
	v_lshlrev_b32_e32 v80, 7, v121
	v_lshl_add_u32 v80, v122, 2, v80
	v_add_u32_e32 v80, 0x18000, v80
	v_add_u32_e32 v82, 16, v80
	v_and_b32_e32 v123, 2, v121
	v_cmp_eq_u32_e64 s[62:63], 0, v123
	v_and_b32_e32 v123, 1, v121
	v_cmp_eq_u32_e64 s[64:65], 0, v123
	v_mov_b32_e32 v0, 0
	v_mov_b32_e32 v1, 0
	v_mov_b32_e32 v2, 0
	v_mov_b32_e32 v3, 0
	v_mov_b32_e32 v4, 0
	v_mov_b32_e32 v5, 0
	v_mov_b32_e32 v6, 0
	v_mov_b32_e32 v7, 0
	v_mov_b32_e32 v92, 0
	v_mov_b32_e32 v93, 0
	s_barrier
	s_barrier
.Lsc_cloop:
	ds_read_b128 v[8:11], v78 offset:0
	ds_read_b128 v[12:15], v78 offset:256
	ds_read_b128 v[16:19], v78 offset:512
	ds_read_b128 v[20:23], v78 offset:768
	ds_read_b128 v[24:27], v78 offset:1024
	ds_read2st64_b32 v[48:49], v79 offset0:5 offset1:11
	ds_read2st64_b32 v[52:53], v81 offset0:5 offset1:11
	s_waitcnt lgkmcnt(0)
	ds_read_b128 v[28:31], v78 offset:1536
	ds_read_b128 v[32:35], v78 offset:1792
	ds_read_b128 v[36:39], v78 offset:2048
	ds_read_b128 v[40:43], v78 offset:2304
	ds_read_b128 v[44:47], v78 offset:2560
	v_pk_mul_f32 v[56:57], v[0:1], v[8:9]
	v_pk_mul_f32 v[58:59], v[4:5], v[8:9]
	v_pk_mul_f32 v[64:65], v[20:21], v[48:49] op_sel_hi:[1,0]
	v_pk_mul_f32 v[68:69], v[20:21], v[52:53] op_sel_hi:[1,0]
	v_pk_fma_f32 v[56:57], v[2:3], v[10:11], v[56:57]
	v_pk_fma_f32 v[58:59], v[6:7], v[10:11], v[58:59]
	v_pk_mul_f32 v[66:67], v[22:23], v[48:49] op_sel_hi:[1,0]
	v_pk_mul_f32 v[70:71], v[22:23], v[52:53] op_sel_hi:[1,0]
	v_add_f32_e32 v72, v56, v57
	v_add_f32_e32 v73, v58, v59
	v_pk_fma_f32 v[0:1], v[0:1], v[12:13], v[64:65]
	v_add_f32_dpp v72, v72, v72 quad_perm:[1,0,3,2] row_mask:0xf bank_mask:0xf bound_ctrl:1
	v_add_f32_dpp v73, v73, v73 quad_perm:[1,0,3,2] row_mask:0xf bank_mask:0xf bound_ctrl:1
	v_pk_fma_f32 v[4:5], v[4:5], v[12:13], v[68:69]
	v_add_f32_dpp v72, v72, v72 quad_perm:[2,3,0,1] row_mask:0xf bank_mask:0xf bound_ctrl:1
	v_add_f32_dpp v73, v73, v73 quad_perm:[2,3,0,1] row_mask:0xf bank_mask:0xf bound_ctrl:1
	v_pk_fma_f32 v[2:3], v[2:3], v[14:15], v[66:67]
	v_add_f32_dpp v72, v72, v72 row_half_mirror row_mask:0xf bank_mask:0xf bound_ctrl:1
	v_add_f32_dpp v73, v73, v73 row_half_mirror row_mask:0xf bank_mask:0xf bound_ctrl:1
	v_pk_fma_f32 v[6:7], v[6:7], v[14:15], v[70:71]
	v_add_f32_dpp v74, v72, v72 row_mirror row_mask:0xf bank_mask:0xf bound_ctrl:1
	v_add_f32_dpp v76, v73, v73 row_mirror row_mask:0xf bank_mask:0xf bound_ctrl:1
	v_pk_fma_f32 v[0:1], v[16:17], v[74:75], v[0:1] op_sel_hi:[1,0,1]
	v_pk_fma_f32 v[2:3], v[18:19], v[74:75], v[2:3] op_sel_hi:[1,0,1]
	v_pk_fma_f32 v[4:5], v[16:17], v[76:77], v[4:5] op_sel_hi:[1,0,1]
	v_pk_fma_f32 v[6:7], v[18:19], v[76:77], v[6:7] op_sel_hi:[1,0,1]
	v_pk_mul_f32 v[60:61], v[0:1], v[24:25]
	v_pk_mul_f32 v[62:63], v[4:5], v[24:25]
	v_pk_fma_f32 v[60:61], v[2:3], v[26:27], v[60:61]
	v_pk_fma_f32 v[62:63], v[6:7], v[26:27], v[62:63]
	v_add_f32_e32 v98, v60, v61
	v_add_f32_e32 v114, v62, v63
	s_waitcnt lgkmcnt(0)
	ds_read_b128 v[8:11], v78 offset:3072
	ds_read_b128 v[12:15], v78 offset:3328
	ds_read_b128 v[16:19], v78 offset:3584
	ds_read_b128 v[20:23], v78 offset:3840
	ds_read_b128 v[24:27], v78 offset:4096
	ds_read2st64_b32 v[50:51], v79 offset0:17 offset1:23
	ds_read2st64_b32 v[54:55], v81 offset0:17 offset1:23
	v_pk_mul_f32 v[56:57], v[0:1], v[28:29]
	v_pk_mul_f32 v[58:59], v[4:5], v[28:29]
	v_pk_mul_f32 v[64:65], v[40:41], v[48:49] op_sel:[0,1] op_sel_hi:[1,1]
	v_pk_mul_f32 v[68:69], v[40:41], v[52:53] op_sel:[0,1] op_sel_hi:[1,1]
	v_pk_fma_f32 v[56:57], v[2:3], v[30:31], v[56:57]
	v_pk_fma_f32 v[58:59], v[6:7], v[30:31], v[58:59]
	v_pk_mul_f32 v[66:67], v[42:43], v[48:49] op_sel:[0,1] op_sel_hi:[1,1]
	v_pk_mul_f32 v[70:71], v[42:43], v[52:53] op_sel:[0,1] op_sel_hi:[1,1]
	v_add_f32_e32 v72, v56, v57
	v_add_f32_e32 v73, v58, v59
	v_pk_fma_f32 v[0:1], v[0:1], v[32:33], v[64:65]
	v_add_f32_dpp v72, v72, v72 quad_perm:[1,0,3,2] row_mask:0xf bank_mask:0xf bound_ctrl:1
	v_add_f32_dpp v73, v73, v73 quad_perm:[1,0,3,2] row_mask:0xf bank_mask:0xf bound_ctrl:1
	v_pk_fma_f32 v[4:5], v[4:5], v[32:33], v[68:69]
	v_add_f32_dpp v72, v72, v72 quad_perm:[2,3,0,1] row_mask:0xf bank_mask:0xf bound_ctrl:1
	v_add_f32_dpp v73, v73, v73 quad_perm:[2,3,0,1] row_mask:0xf bank_mask:0xf bound_ctrl:1
	v_pk_fma_f32 v[2:3], v[2:3], v[34:35], v[66:67]
	v_add_f32_dpp v72, v72, v72 row_half_mirror row_mask:0xf bank_mask:0xf bound_ctrl:1
	v_add_f32_dpp v73, v73, v73 row_half_mirror row_mask:0xf bank_mask:0xf bound_ctrl:1
	v_pk_fma_f32 v[6:7], v[6:7], v[34:35], v[70:71]
	v_add_f32_dpp v74, v72, v72 row_mirror row_mask:0xf bank_mask:0xf bound_ctrl:1
	v_add_f32_dpp v76, v73, v73 row_mirror row_mask:0xf bank_mask:0xf bound_ctrl:1
	v_pk_fma_f32 v[0:1], v[36:37], v[74:75], v[0:1] op_sel_hi:[1,0,1]
	v_pk_fma_f32 v[2:3], v[38:39], v[74:75], v[2:3] op_sel_hi:[1,0,1]
	v_pk_fma_f32 v[4:5], v[36:37], v[76:77], v[4:5] op_sel_hi:[1,0,1]
	v_pk_fma_f32 v[6:7], v[38:39], v[76:77], v[6:7] op_sel_hi:[1,0,1]
	v_pk_mul_f32 v[60:61], v[0:1], v[44:45]
	v_pk_mul_f32 v[62:63], v[4:5], v[44:45]
	v_pk_fma_f32 v[60:61], v[2:3], v[46:47], v[60:61]
	v_pk_fma_f32 v[62:63], v[6:7], v[46:47], v[62:63]
	v_add_f32_e32 v99, v60, v61
	v_add_f32_e32 v115, v62, v63
	s_waitcnt lgkmcnt(0)
; DEV void scan_tile(const Params& p, int l, int tile, char* smem) {
;     ...
;       auto ldops = [&](ScanOps& o, int sl) {
;         const f32x4* b4 = (const f32x4*)(cb + sl * 384);
;         o.nkk0 = b4[cg * 2]; o.nkk1 = b4[cg * 2 + 1];
;         o.w0 = b4[16 + cg * 2]; o.w1 = b4[16 + cg * 2 + 1];
;         o.kka0 = b4[32 + cg * 2]; o.kka1 = b4[32 + cg * 2 + 1];
;         o.kd0 = b4[48 + cg * 2]; o.kd1 = b4[48 + cg * 2 + 1];
;         o.r0 = b4[64 + cg * 2]; o.r1 = b4[64 + cg * 2 + 1];
;         o.v = cb[sl * 384 + vo];
;       };
;       float ykeep = 0.f;
;       auto step = [&](const ScanOps& o, int sl) {
;         const f32x4 sA = S0 * o.nkk0 + S1 * o.nkk1;
;         const float sa = red8((sA[0] + sA[1]) + (sA[2] + sA[3]));
;         S0 = S0 * o.w0 + (o.kka0 * sa + o.kd0 * o.v);
;         S1 = S1 * o.w1 + (o.kka1 * sa + o.kd1 * o.v);
;         const f32x4 yA = S0 * o.r0 + S1 * o.r1;
;         const float y = red8((yA[0] + yA[1]) + (yA[2] + yA[3]));
	ds_read_b128 v[28:31], v78 offset:4608
	ds_read_b128 v[32:35], v78 offset:4864
	ds_read_b128 v[36:39], v78 offset:5120
	ds_read_b128 v[40:43], v78 offset:5376
	ds_read_b128 v[44:47], v78 offset:5632
	v_pk_mul_f32 v[56:57], v[0:1], v[8:9]
	v_pk_mul_f32 v[58:59], v[4:5], v[8:9]
	v_pk_mul_f32 v[64:65], v[20:21], v[50:51] op_sel_hi:[1,0]
	v_pk_mul_f32 v[68:69], v[20:21], v[54:55] op_sel_hi:[1,0]
	v_pk_fma_f32 v[56:57], v[2:3], v[10:11], v[56:57]
	v_pk_fma_f32 v[58:59], v[6:7], v[10:11], v[58:59]
	v_pk_mul_f32 v[66:67], v[22:23], v[50:51] op_sel_hi:[1,0]
	v_pk_mul_f32 v[70:71], v[22:23], v[54:55] op_sel_hi:[1,0]
	v_add_f32_e32 v72, v56, v57
	v_add_f32_e32 v73, v58, v59
	v_pk_fma_f32 v[0:1], v[0:1], v[12:13], v[64:65]
	v_add_f32_dpp v72, v72, v72 quad_perm:[1,0,3,2] row_mask:0xf bank_mask:0xf bound_ctrl:1
	v_add_f32_dpp v73, v73, v73 quad_perm:[1,0,3,2] row_mask:0xf bank_mask:0xf bound_ctrl:1
	v_pk_fma_f32 v[4:5], v[4:5], v[12:13], v[68:69]
	v_add_f32_dpp v72, v72, v72 quad_perm:[2,3,0,1] row_mask:0xf bank_mask:0xf bound_ctrl:1
	v_add_f32_dpp v73, v73, v73 quad_perm:[2,3,0,1] row_mask:0xf bank_mask:0xf bound_ctrl:1
	v_pk_fma_f32 v[2:3], v[2:3], v[14:15], v[66:67]
	v_add_f32_dpp v72, v72, v72 row_half_mirror row_mask:0xf bank_mask:0xf bound_ctrl:1
	v_add_f32_dpp v73, v73, v73 row_half_mirror row_mask:0xf bank_mask:0xf bound_ctrl:1
	v_pk_fma_f32 v[6:7], v[6:7], v[14:15], v[70:71]
	v_add_f32_dpp v74, v72, v72 row_mirror row_mask:0xf bank_mask:0xf bound_ctrl:1
	v_add_f32_dpp v76, v73, v73 row_mirror row_mask:0xf bank_mask:0xf bound_ctrl:1
	v_pk_fma_f32 v[0:1], v[16:17], v[74:75], v[0:1] op_sel_hi:[1,0,1]
	v_pk_fma_f32 v[2:3], v[18:19], v[74:75], v[2:3] op_sel_hi:[1,0,1]
	v_pk_fma_f32 v[4:5], v[16:17], v[76:77], v[4:5] op_sel_hi:[1,0,1]
	v_pk_fma_f32 v[6:7], v[18:19], v[76:77], v[6:7] op_sel_hi:[1,0,1]
	v_pk_mul_f32 v[60:61], v[0:1], v[24:25]
	v_pk_mul_f32 v[62:63], v[4:5], v[24:25]
	v_pk_fma_f32 v[60:61], v[2:3], v[26:27], v[60:61]
	v_pk_fma_f32 v[62:63], v[6:7], v[26:27], v[62:63]
	v_add_f32_e32 v100, v60, v61
	v_add_f32_e32 v116, v62, v63
	s_waitcnt lgkmcnt(0)
	ds_read_b128 v[8:11], v78 offset:6144
	ds_read_b128 v[12:15], v78 offset:6400
	ds_read_b128 v[16:19], v78 offset:6656
	ds_read_b128 v[20:23], v78 offset:6912
	ds_read_b128 v[24:27], v78 offset:7168
	ds_read2st64_b32 v[48:49], v79 offset0:29 offset1:35
	ds_read2st64_b32 v[52:53], v81 offset0:29 offset1:35
	v_pk_mul_f32 v[56:57], v[0:1], v[28:29]
	v_pk_mul_f32 v[58:59], v[4:5], v[28:29]
	v_pk_mul_f32 v[64:65], v[40:41], v[50:51] op_sel:[0,1] op_sel_hi:[1,1]
	v_pk_mul_f32 v[68:69], v[40:41], v[54:55] op_sel:[0,1] op_sel_hi:[1,1]
	v_pk_fma_f32 v[56:57], v[2:3], v[30:31], v[56:57]
	v_pk_fma_f32 v[58:59], v[6:7], v[30:31], v[58:59]
	v_pk_mul_f32 v[66:67], v[42:43], v[50:51] op_sel:[0,1] op_sel_hi:[1,1]
	v_pk_mul_f32 v[70:71], v[42:43], v[54:55] op_sel:[0,1] op_sel_hi:[1,1]
	v_add_f32_e32 v72, v56, v57
	v_add_f32_e32 v73, v58, v59
	v_pk_fma_f32 v[0:1], v[0:1], v[32:33], v[64:65]
	v_add_f32_dpp v72, v72, v72 quad_perm:[1,0,3,2] row_mask:0xf bank_mask:0xf bound_ctrl:1
	v_add_f32_dpp v73, v73, v73 quad_perm:[1,0,3,2] row_mask:0xf bank_mask:0xf bound_ctrl:1
	v_pk_fma_f32 v[4:5], v[4:5], v[32:33], v[68:69]
	v_add_f32_dpp v72, v72, v72 quad_perm:[2,3,0,1] row_mask:0xf bank_mask:0xf bound_ctrl:1
	v_add_f32_dpp v73, v73, v73 quad_perm:[2,3,0,1] row_mask:0xf bank_mask:0xf bound_ctrl:1
	v_pk_fma_f32 v[2:3], v[2:3], v[34:35], v[66:67]
	v_add_f32_dpp v72, v72, v72 row_half_mirror row_mask:0xf bank_mask:0xf bound_ctrl:1
	v_add_f32_dpp v73, v73, v73 row_half_mirror row_mask:0xf bank_mask:0xf bound_ctrl:1
	v_pk_fma_f32 v[6:7], v[6:7], v[34:35], v[70:71]
	v_add_f32_dpp v74, v72, v72 row_mirror row_mask:0xf bank_mask:0xf bound_ctrl:1
	v_add_f32_dpp v76, v73, v73 row_mirror row_mask:0xf bank_mask:0xf bound_ctrl:1
	v_pk_fma_f32 v[0:1], v[36:37], v[74:75], v[0:1] op_sel_hi:[1,0,1]
	v_pk_fma_f32 v[2:3], v[38:39], v[74:75], v[2:3] op_sel_hi:[1,0,1]
	v_pk_fma_f32 v[4:5], v[36:37], v[76:77], v[4:5] op_sel_hi:[1,0,1]
	v_pk_fma_f32 v[6:7], v[38:39], v[76:77], v[6:7] op_sel_hi:[1,0,1]
	v_pk_mul_f32 v[60:61], v[0:1], v[44:45]
	v_pk_mul_f32 v[62:63], v[4:5], v[44:45]
	v_pk_fma_f32 v[60:61], v[2:3], v[46:47], v[60:61]
	v_pk_fma_f32 v[62:63], v[6:7], v[46:47], v[62:63]
	v_add_f32_e32 v101, v60, v61
	v_add_f32_e32 v117, v62, v63
	s_waitcnt lgkmcnt(0)
	ds_read_b128 v[28:31], v78 offset:7680
	ds_read_b128 v[32:35], v78 offset:7936
	ds_read_b128 v[36:39], v78 offset:8192
	ds_read_b128 v[40:43], v78 offset:8448
	ds_read_b128 v[44:47], v78 offset:8704
	v_pk_mul_f32 v[56:57], v[0:1], v[8:9]
	v_pk_mul_f32 v[58:59], v[4:5], v[8:9]
	v_pk_mul_f32 v[64:65], v[20:21], v[48:49] op_sel_hi:[1,0]
	v_pk_mul_f32 v[68:69], v[20:21], v[52:53] op_sel_hi:[1,0]
	v_pk_fma_f32 v[56:57], v[2:3], v[10:11], v[56:57]
	v_pk_fma_f32 v[58:59], v[6:7], v[10:11], v[58:59]
	v_pk_mul_f32 v[66:67], v[22:23], v[48:49] op_sel_hi:[1,0]
	v_pk_mul_f32 v[70:71], v[22:23], v[52:53] op_sel_hi:[1,0]
	v_add_f32_e32 v72, v56, v57
	v_add_f32_e32 v73, v58, v59
	v_pk_fma_f32 v[0:1], v[0:1], v[12:13], v[64:65]
	v_add_f32_dpp v72, v72, v72 quad_perm:[1,0,3,2] row_mask:0xf bank_mask:0xf bound_ctrl:1
	v_add_f32_dpp v73, v73, v73 quad_perm:[1,0,3,2] row_mask:0xf bank_mask:0xf bound_ctrl:1
	v_pk_fma_f32 v[4:5], v[4:5], v[12:13], v[68:69]
	v_add_f32_dpp v72, v72, v72 quad_perm:[2,3,0,1] row_mask:0xf bank_mask:0xf bound_ctrl:1
	v_add_f32_dpp v73, v73, v73 quad_perm:[2,3,0,1] row_mask:0xf bank_mask:0xf bound_ctrl:1
	v_pk_fma_f32 v[2:3], v[2:3], v[14:15], v[66:67]
	v_add_f32_dpp v72, v72, v72 row_half_mirror row_mask:0xf bank_mask:0xf bound_ctrl:1
	v_add_f32_dpp v73, v73, v73 row_half_mirror row_mask:0xf bank_mask:0xf bound_ctrl:1
	v_pk_fma_f32 v[6:7], v[6:7], v[14:15], v[70:71]
	v_add_f32_dpp v74, v72, v72 row_mirror row_mask:0xf bank_mask:0xf bound_ctrl:1
	v_add_f32_dpp v76, v73, v73 row_mirror row_mask:0xf bank_mask:0xf bound_ctrl:1
	v_pk_fma_f32 v[0:1], v[16:17], v[74:75], v[0:1] op_sel_hi:[1,0,1]
	v_pk_fma_f32 v[2:3], v[18:19], v[74:75], v[2:3] op_sel_hi:[1,0,1]
	v_pk_fma_f32 v[4:5], v[16:17], v[76:77], v[4:5] op_sel_hi:[1,0,1]
	v_pk_fma_f32 v[6:7], v[18:19], v[76:77], v[6:7] op_sel_hi:[1,0,1]
	v_pk_mul_f32 v[60:61], v[0:1], v[24:25]
	v_pk_mul_f32 v[62:63], v[4:5], v[24:25]
	v_pk_fma_f32 v[60:61], v[2:3], v[26:27], v[60:61]
	v_pk_fma_f32 v[62:63], v[6:7], v[26:27], v[62:63]
	v_add_f32_e32 v102, v60, v61
	v_add_f32_e32 v118, v62, v63
	s_waitcnt lgkmcnt(0)
; DEV void scan_tile(const Params& p, int l, int tile, char* smem) {
;     ...
;       auto ldops = [&](ScanOps& o, int sl) {
;         const f32x4* b4 = (const f32x4*)(cb + sl * 384);
;         o.nkk0 = b4[cg * 2]; o.nkk1 = b4[cg * 2 + 1];
;         o.w0 = b4[16 + cg * 2]; o.w1 = b4[16 + cg * 2 + 1];
;         o.kka0 = b4[32 + cg * 2]; o.kka1 = b4[32 + cg * 2 + 1];
;         o.kd0 = b4[48 + cg * 2]; o.kd1 = b4[48 + cg * 2 + 1];
;         o.r0 = b4[64 + cg * 2]; o.r1 = b4[64 + cg * 2 + 1];
;         o.v = cb[sl * 384 + vo];
;       };
;       float ykeep = 0.f;
;       auto step = [&](const ScanOps& o, int sl) {
;         const f32x4 sA = S0 * o.nkk0 + S1 * o.nkk1;
;         const float sa = red8((sA[0] + sA[1]) + (sA[2] + sA[3]));
;         S0 = S0 * o.w0 + (o.kka0 * sa + o.kd0 * o.v);
;         S1 = S1 * o.w1 + (o.kka1 * sa + o.kd1 * o.v);
;         const f32x4 yA = S0 * o.r0 + S1 * o.r1;
;         const float y = red8((yA[0] + yA[1]) + (yA[2] + yA[3]));
	ds_read_b128 v[8:11], v78 offset:9216
	ds_read_b128 v[12:15], v78 offset:9472
	ds_read_b128 v[16:19], v78 offset:9728
	ds_read_b128 v[20:23], v78 offset:9984
	ds_read_b128 v[24:27], v78 offset:10240
	ds_read2st64_b32 v[50:51], v79 offset0:41 offset1:47
	ds_read2st64_b32 v[54:55], v81 offset0:41 offset1:47
	v_pk_mul_f32 v[56:57], v[0:1], v[28:29]
	v_pk_mul_f32 v[58:59], v[4:5], v[28:29]
	v_pk_mul_f32 v[64:65], v[40:41], v[48:49] op_sel:[0,1] op_sel_hi:[1,1]
	v_pk_mul_f32 v[68:69], v[40:41], v[52:53] op_sel:[0,1] op_sel_hi:[1,1]
	v_pk_fma_f32 v[56:57], v[2:3], v[30:31], v[56:57]
	v_pk_fma_f32 v[58:59], v[6:7], v[30:31], v[58:59]
	v_pk_mul_f32 v[66:67], v[42:43], v[48:49] op_sel:[0,1] op_sel_hi:[1,1]
	v_pk_mul_f32 v[70:71], v[42:43], v[52:53] op_sel:[0,1] op_sel_hi:[1,1]
	v_add_f32_e32 v72, v56, v57
	v_add_f32_e32 v73, v58, v59
	v_pk_fma_f32 v[0:1], v[0:1], v[32:33], v[64:65]
	v_add_f32_dpp v72, v72, v72 quad_perm:[1,0,3,2] row_mask:0xf bank_mask:0xf bound_ctrl:1
	v_add_f32_dpp v73, v73, v73 quad_perm:[1,0,3,2] row_mask:0xf bank_mask:0xf bound_ctrl:1
	v_pk_fma_f32 v[4:5], v[4:5], v[32:33], v[68:69]
	v_add_f32_dpp v72, v72, v72 quad_perm:[2,3,0,1] row_mask:0xf bank_mask:0xf bound_ctrl:1
	v_add_f32_dpp v73, v73, v73 quad_perm:[2,3,0,1] row_mask:0xf bank_mask:0xf bound_ctrl:1
	v_pk_fma_f32 v[2:3], v[2:3], v[34:35], v[66:67]
	v_add_f32_dpp v72, v72, v72 row_half_mirror row_mask:0xf bank_mask:0xf bound_ctrl:1
	v_add_f32_dpp v73, v73, v73 row_half_mirror row_mask:0xf bank_mask:0xf bound_ctrl:1
	v_pk_fma_f32 v[6:7], v[6:7], v[34:35], v[70:71]
	v_add_f32_dpp v74, v72, v72 row_mirror row_mask:0xf bank_mask:0xf bound_ctrl:1
	v_add_f32_dpp v76, v73, v73 row_mirror row_mask:0xf bank_mask:0xf bound_ctrl:1
	v_pk_fma_f32 v[0:1], v[36:37], v[74:75], v[0:1] op_sel_hi:[1,0,1]
	v_pk_fma_f32 v[2:3], v[38:39], v[74:75], v[2:3] op_sel_hi:[1,0,1]
	v_pk_fma_f32 v[4:5], v[36:37], v[76:77], v[4:5] op_sel_hi:[1,0,1]
	v_pk_fma_f32 v[6:7], v[38:39], v[76:77], v[6:7] op_sel_hi:[1,0,1]
	v_pk_mul_f32 v[60:61], v[0:1], v[44:45]
	v_pk_mul_f32 v[62:63], v[4:5], v[44:45]
	v_pk_fma_f32 v[60:61], v[2:3], v[46:47], v[60:61]
	v_pk_fma_f32 v[62:63], v[6:7], v[46:47], v[62:63]
	v_add_f32_e32 v103, v60, v61
	v_add_f32_e32 v119, v62, v63
	s_waitcnt lgkmcnt(0)
	ds_read_b128 v[28:31], v78 offset:10752
	ds_read_b128 v[32:35], v78 offset:11008
	ds_read_b128 v[36:39], v78 offset:11264
	ds_read_b128 v[40:43], v78 offset:11520
	ds_read_b128 v[44:47], v78 offset:11776
	v_pk_mul_f32 v[56:57], v[0:1], v[8:9]
	v_pk_mul_f32 v[58:59], v[4:5], v[8:9]
	v_pk_mul_f32 v[64:65], v[20:21], v[50:51] op_sel_hi:[1,0]
	v_pk_mul_f32 v[68:69], v[20:21], v[54:55] op_sel_hi:[1,0]
	v_pk_fma_f32 v[56:57], v[2:3], v[10:11], v[56:57]
	v_pk_fma_f32 v[58:59], v[6:7], v[10:11], v[58:59]
	v_pk_mul_f32 v[66:67], v[22:23], v[50:51] op_sel_hi:[1,0]
	v_pk_mul_f32 v[70:71], v[22:23], v[54:55] op_sel_hi:[1,0]
	v_add_f32_e32 v72, v56, v57
	v_add_f32_e32 v73, v58, v59
	v_pk_fma_f32 v[0:1], v[0:1], v[12:13], v[64:65]
	v_add_f32_dpp v72, v72, v72 quad_perm:[1,0,3,2] row_mask:0xf bank_mask:0xf bound_ctrl:1
	v_add_f32_dpp v73, v73, v73 quad_perm:[1,0,3,2] row_mask:0xf bank_mask:0xf bound_ctrl:1
	v_pk_fma_f32 v[4:5], v[4:5], v[12:13], v[68:69]
	v_add_f32_dpp v72, v72, v72 quad_perm:[2,3,0,1] row_mask:0xf bank_mask:0xf bound_ctrl:1
	v_add_f32_dpp v73, v73, v73 quad_perm:[2,3,0,1] row_mask:0xf bank_mask:0xf bound_ctrl:1
	v_pk_fma_f32 v[2:3], v[2:3], v[14:15], v[66:67]
	v_add_f32_dpp v72, v72, v72 row_half_mirror row_mask:0xf bank_mask:0xf bound_ctrl:1
	v_add_f32_dpp v73, v73, v73 row_half_mirror row_mask:0xf bank_mask:0xf bound_ctrl:1
	v_pk_fma_f32 v[6:7], v[6:7], v[14:15], v[70:71]
	v_add_f32_dpp v74, v72, v72 row_mirror row_mask:0xf bank_mask:0xf bound_ctrl:1
	v_add_f32_dpp v76, v73, v73 row_mirror row_mask:0xf bank_mask:0xf bound_ctrl:1
	v_pk_fma_f32 v[0:1], v[16:17], v[74:75], v[0:1] op_sel_hi:[1,0,1]
	v_pk_fma_f32 v[2:3], v[18:19], v[74:75], v[2:3] op_sel_hi:[1,0,1]
	v_pk_fma_f32 v[4:5], v[16:17], v[76:77], v[4:5] op_sel_hi:[1,0,1]
	v_pk_fma_f32 v[6:7], v[18:19], v[76:77], v[6:7] op_sel_hi:[1,0,1]
	v_pk_mul_f32 v[60:61], v[0:1], v[24:25]
	v_pk_mul_f32 v[62:63], v[4:5], v[24:25]
	v_pk_fma_f32 v[60:61], v[2:3], v[26:27], v[60:61]
	v_pk_fma_f32 v[62:63], v[6:7], v[26:27], v[62:63]
	v_add_f32_e32 v104, v60, v61
	v_add_f32_e32 v120, v62, v63
	s_waitcnt lgkmcnt(0)
	ds_read_b128 v[8:11], v78 offset:12288
	ds_read_b128 v[12:15], v78 offset:12544
	ds_read_b128 v[16:19], v78 offset:12800
	ds_read_b128 v[20:23], v78 offset:13056
	ds_read_b128 v[24:27], v78 offset:13312
	ds_read2st64_b32 v[48:49], v79 offset0:53 offset1:59
	ds_read2st64_b32 v[52:53], v81 offset0:53 offset1:59
	v_pk_mul_f32 v[56:57], v[0:1], v[28:29]
	v_pk_mul_f32 v[58:59], v[4:5], v[28:29]
	v_pk_mul_f32 v[64:65], v[40:41], v[50:51] op_sel:[0,1] op_sel_hi:[1,1]
	v_pk_mul_f32 v[68:69], v[40:41], v[54:55] op_sel:[0,1] op_sel_hi:[1,1]
	v_pk_fma_f32 v[56:57], v[2:3], v[30:31], v[56:57]
	v_pk_fma_f32 v[58:59], v[6:7], v[30:31], v[58:59]
	v_pk_mul_f32 v[66:67], v[42:43], v[50:51] op_sel:[0,1] op_sel_hi:[1,1]
	v_pk_mul_f32 v[70:71], v[42:43], v[54:55] op_sel:[0,1] op_sel_hi:[1,1]
	v_add_f32_e32 v72, v56, v57
	v_add_f32_e32 v73, v58, v59
	v_pk_fma_f32 v[0:1], v[0:1], v[32:33], v[64:65]
	v_add_f32_dpp v72, v72, v72 quad_perm:[1,0,3,2] row_mask:0xf bank_mask:0xf bound_ctrl:1
	v_add_f32_dpp v73, v73, v73 quad_perm:[1,0,3,2] row_mask:0xf bank_mask:0xf bound_ctrl:1
	v_pk_fma_f32 v[4:5], v[4:5], v[32:33], v[68:69]
	v_add_f32_dpp v72, v72, v72 quad_perm:[2,3,0,1] row_mask:0xf bank_mask:0xf bound_ctrl:1
	v_add_f32_dpp v73, v73, v73 quad_perm:[2,3,0,1] row_mask:0xf bank_mask:0xf bound_ctrl:1
	v_pk_fma_f32 v[2:3], v[2:3], v[34:35], v[66:67]
	v_add_f32_dpp v72, v72, v72 row_half_mirror row_mask:0xf bank_mask:0xf bound_ctrl:1
	v_add_f32_dpp v73, v73, v73 row_half_mirror row_mask:0xf bank_mask:0xf bound_ctrl:1
	v_pk_fma_f32 v[6:7], v[6:7], v[34:35], v[70:71]
	v_add_f32_dpp v74, v72, v72 row_mirror row_mask:0xf bank_mask:0xf bound_ctrl:1
	v_add_f32_dpp v76, v73, v73 row_mirror row_mask:0xf bank_mask:0xf bound_ctrl:1
	v_pk_fma_f32 v[0:1], v[36:37], v[74:75], v[0:1] op_sel_hi:[1,0,1]
	v_pk_fma_f32 v[2:3], v[38:39], v[74:75], v[2:3] op_sel_hi:[1,0,1]
	v_pk_fma_f32 v[4:5], v[36:37], v[76:77], v[4:5] op_sel_hi:[1,0,1]
	v_pk_fma_f32 v[6:7], v[38:39], v[76:77], v[6:7] op_sel_hi:[1,0,1]
	v_pk_mul_f32 v[60:61], v[0:1], v[44:45]
	v_pk_mul_f32 v[62:63], v[4:5], v[44:45]
	v_pk_fma_f32 v[60:61], v[2:3], v[46:47], v[60:61]
	v_pk_fma_f32 v[62:63], v[6:7], v[46:47], v[62:63]
	v_add_f32_e32 v105, v60, v61
	v_add_f32_e32 v121, v62, v63
	s_waitcnt lgkmcnt(0)
; DEV void scan_tile(const Params& p, int l, int tile, char* smem) {
;     ...
;       auto ldops = [&](ScanOps& o, int sl) {
;         const f32x4* b4 = (const f32x4*)(cb + sl * 384);
;         o.nkk0 = b4[cg * 2]; o.nkk1 = b4[cg * 2 + 1];
;         o.w0 = b4[16 + cg * 2]; o.w1 = b4[16 + cg * 2 + 1];
;         o.kka0 = b4[32 + cg * 2]; o.kka1 = b4[32 + cg * 2 + 1];
;         o.kd0 = b4[48 + cg * 2]; o.kd1 = b4[48 + cg * 2 + 1];
;         o.r0 = b4[64 + cg * 2]; o.r1 = b4[64 + cg * 2 + 1];
;         o.v = cb[sl * 384 + vo];
;       };
;       float ykeep = 0.f;
;       auto step = [&](const ScanOps& o, int sl) {
;         const f32x4 sA = S0 * o.nkk0 + S1 * o.nkk1;
;         const float sa = red8((sA[0] + sA[1]) + (sA[2] + sA[3]));
;         S0 = S0 * o.w0 + (o.kka0 * sa + o.kd0 * o.v);
;         S1 = S1 * o.w1 + (o.kka1 * sa + o.kd1 * o.v);
;         const f32x4 yA = S0 * o.r0 + S1 * o.r1;
;         const float y = red8((yA[0] + yA[1]) + (yA[2] + yA[3]));
	ds_read_b128 v[28:31], v78 offset:13824
	ds_read_b128 v[32:35], v78 offset:14080
	ds_read_b128 v[36:39], v78 offset:14336
	ds_read_b128 v[40:43], v78 offset:14592
	ds_read_b128 v[44:47], v78 offset:14848
	v_pk_mul_f32 v[56:57], v[0:1], v[8:9]
	v_pk_mul_f32 v[58:59], v[4:5], v[8:9]
	v_pk_mul_f32 v[64:65], v[20:21], v[48:49] op_sel_hi:[1,0]
	v_pk_mul_f32 v[68:69], v[20:21], v[52:53] op_sel_hi:[1,0]
	v_pk_fma_f32 v[56:57], v[2:3], v[10:11], v[56:57]
	v_pk_fma_f32 v[58:59], v[6:7], v[10:11], v[58:59]
	v_pk_mul_f32 v[66:67], v[22:23], v[48:49] op_sel_hi:[1,0]
	v_pk_mul_f32 v[70:71], v[22:23], v[52:53] op_sel_hi:[1,0]
	v_add_f32_e32 v72, v56, v57
	v_add_f32_e32 v73, v58, v59
	v_pk_fma_f32 v[0:1], v[0:1], v[12:13], v[64:65]
	v_add_f32_dpp v72, v72, v72 quad_perm:[1,0,3,2] row_mask:0xf bank_mask:0xf bound_ctrl:1
	v_add_f32_dpp v73, v73, v73 quad_perm:[1,0,3,2] row_mask:0xf bank_mask:0xf bound_ctrl:1
	v_pk_fma_f32 v[4:5], v[4:5], v[12:13], v[68:69]
	v_add_f32_dpp v72, v72, v72 quad_perm:[2,3,0,1] row_mask:0xf bank_mask:0xf bound_ctrl:1
	v_add_f32_dpp v73, v73, v73 quad_perm:[2,3,0,1] row_mask:0xf bank_mask:0xf bound_ctrl:1
	v_pk_fma_f32 v[2:3], v[2:3], v[14:15], v[66:67]
	v_add_f32_dpp v72, v72, v72 row_half_mirror row_mask:0xf bank_mask:0xf bound_ctrl:1
	v_add_f32_dpp v73, v73, v73 row_half_mirror row_mask:0xf bank_mask:0xf bound_ctrl:1
	v_pk_fma_f32 v[6:7], v[6:7], v[14:15], v[70:71]
	v_add_f32_dpp v74, v72, v72 row_mirror row_mask:0xf bank_mask:0xf bound_ctrl:1
	v_add_f32_dpp v76, v73, v73 row_mirror row_mask:0xf bank_mask:0xf bound_ctrl:1
	v_pk_fma_f32 v[0:1], v[16:17], v[74:75], v[0:1] op_sel_hi:[1,0,1]
	v_pk_fma_f32 v[2:3], v[18:19], v[74:75], v[2:3] op_sel_hi:[1,0,1]
	v_pk_fma_f32 v[4:5], v[16:17], v[76:77], v[4:5] op_sel_hi:[1,0,1]
	v_pk_fma_f32 v[6:7], v[18:19], v[76:77], v[6:7] op_sel_hi:[1,0,1]
	v_pk_mul_f32 v[60:61], v[0:1], v[24:25]
	v_pk_mul_f32 v[62:63], v[4:5], v[24:25]
	v_pk_fma_f32 v[60:61], v[2:3], v[26:27], v[60:61]
	v_pk_fma_f32 v[62:63], v[6:7], v[26:27], v[62:63]
	v_add_f32_e32 v106, v60, v61
	v_add_f32_e32 v122, v62, v63
	s_waitcnt lgkmcnt(0)
	ds_read_b128 v[8:11], v78 offset:15360
	ds_read_b128 v[12:15], v78 offset:15616
	ds_read_b128 v[16:19], v78 offset:15872
	ds_read_b128 v[20:23], v78 offset:16128
	ds_read_b128 v[24:27], v78 offset:16384
	ds_read2st64_b32 v[50:51], v79 offset0:65 offset1:71
	ds_read2st64_b32 v[54:55], v81 offset0:65 offset1:71
	v_pk_mul_f32 v[56:57], v[0:1], v[28:29]
	v_pk_mul_f32 v[58:59], v[4:5], v[28:29]
	v_pk_mul_f32 v[64:65], v[40:41], v[48:49] op_sel:[0,1] op_sel_hi:[1,1]
	v_pk_mul_f32 v[68:69], v[40:41], v[52:53] op_sel:[0,1] op_sel_hi:[1,1]
	v_pk_fma_f32 v[56:57], v[2:3], v[30:31], v[56:57]
	v_pk_fma_f32 v[58:59], v[6:7], v[30:31], v[58:59]
	v_pk_mul_f32 v[66:67], v[42:43], v[48:49] op_sel:[0,1] op_sel_hi:[1,1]
	v_pk_mul_f32 v[70:71], v[42:43], v[52:53] op_sel:[0,1] op_sel_hi:[1,1]
	v_add_f32_e32 v72, v56, v57
	v_add_f32_e32 v73, v58, v59
	v_pk_fma_f32 v[0:1], v[0:1], v[32:33], v[64:65]
	v_add_f32_dpp v72, v72, v72 quad_perm:[1,0,3,2] row_mask:0xf bank_mask:0xf bound_ctrl:1
	v_add_f32_dpp v73, v73, v73 quad_perm:[1,0,3,2] row_mask:0xf bank_mask:0xf bound_ctrl:1
	v_pk_fma_f32 v[4:5], v[4:5], v[32:33], v[68:69]
	v_add_f32_dpp v72, v72, v72 quad_perm:[2,3,0,1] row_mask:0xf bank_mask:0xf bound_ctrl:1
	v_add_f32_dpp v73, v73, v73 quad_perm:[2,3,0,1] row_mask:0xf bank_mask:0xf bound_ctrl:1
	v_pk_fma_f32 v[2:3], v[2:3], v[34:35], v[66:67]
	v_add_f32_dpp v72, v72, v72 row_half_mirror row_mask:0xf bank_mask:0xf bound_ctrl:1
	v_add_f32_dpp v73, v73, v73 row_half_mirror row_mask:0xf bank_mask:0xf bound_ctrl:1
	v_pk_fma_f32 v[6:7], v[6:7], v[34:35], v[70:71]
	v_add_f32_dpp v74, v72, v72 row_mirror row_mask:0xf bank_mask:0xf bound_ctrl:1
	v_add_f32_dpp v76, v73, v73 row_mirror row_mask:0xf bank_mask:0xf bound_ctrl:1
	v_pk_fma_f32 v[0:1], v[36:37], v[74:75], v[0:1] op_sel_hi:[1,0,1]
	v_pk_fma_f32 v[2:3], v[38:39], v[74:75], v[2:3] op_sel_hi:[1,0,1]
	v_pk_fma_f32 v[4:5], v[36:37], v[76:77], v[4:5] op_sel_hi:[1,0,1]
	v_pk_fma_f32 v[6:7], v[38:39], v[76:77], v[6:7] op_sel_hi:[1,0,1]
	v_pk_mul_f32 v[60:61], v[0:1], v[44:45]
	v_pk_mul_f32 v[62:63], v[4:5], v[44:45]
	v_pk_fma_f32 v[60:61], v[2:3], v[46:47], v[60:61]
	v_pk_fma_f32 v[62:63], v[6:7], v[46:47], v[62:63]
	v_add_f32_e32 v107, v60, v61
	v_add_f32_e32 v123, v62, v63
	s_waitcnt lgkmcnt(0)
	ds_read_b128 v[28:31], v78 offset:16896
	ds_read_b128 v[32:35], v78 offset:17152
	ds_read_b128 v[36:39], v78 offset:17408
	ds_read_b128 v[40:43], v78 offset:17664
	ds_read_b128 v[44:47], v78 offset:17920
	v_pk_mul_f32 v[56:57], v[0:1], v[8:9]
	v_pk_mul_f32 v[58:59], v[4:5], v[8:9]
	v_pk_mul_f32 v[64:65], v[20:21], v[50:51] op_sel_hi:[1,0]
	v_pk_mul_f32 v[68:69], v[20:21], v[54:55] op_sel_hi:[1,0]
	v_pk_fma_f32 v[56:57], v[2:3], v[10:11], v[56:57]
	v_pk_fma_f32 v[58:59], v[6:7], v[10:11], v[58:59]
	v_pk_mul_f32 v[66:67], v[22:23], v[50:51] op_sel_hi:[1,0]
	v_pk_mul_f32 v[70:71], v[22:23], v[54:55] op_sel_hi:[1,0]
	v_add_f32_e32 v72, v56, v57
	v_add_f32_e32 v73, v58, v59
	v_pk_fma_f32 v[0:1], v[0:1], v[12:13], v[64:65]
	v_add_f32_dpp v72, v72, v72 quad_perm:[1,0,3,2] row_mask:0xf bank_mask:0xf bound_ctrl:1
	v_add_f32_dpp v73, v73, v73 quad_perm:[1,0,3,2] row_mask:0xf bank_mask:0xf bound_ctrl:1
	v_pk_fma_f32 v[4:5], v[4:5], v[12:13], v[68:69]
	v_add_f32_dpp v72, v72, v72 quad_perm:[2,3,0,1] row_mask:0xf bank_mask:0xf bound_ctrl:1
	v_add_f32_dpp v73, v73, v73 quad_perm:[2,3,0,1] row_mask:0xf bank_mask:0xf bound_ctrl:1
	v_pk_fma_f32 v[2:3], v[2:3], v[14:15], v[66:67]
	v_add_f32_dpp v72, v72, v72 row_half_mirror row_mask:0xf bank_mask:0xf bound_ctrl:1
	v_add_f32_dpp v73, v73, v73 row_half_mirror row_mask:0xf bank_mask:0xf bound_ctrl:1
	v_pk_fma_f32 v[6:7], v[6:7], v[14:15], v[70:71]
	v_add_f32_dpp v74, v72, v72 row_mirror row_mask:0xf bank_mask:0xf bound_ctrl:1
	v_add_f32_dpp v76, v73, v73 row_mirror row_mask:0xf bank_mask:0xf bound_ctrl:1
	v_pk_fma_f32 v[0:1], v[16:17], v[74:75], v[0:1] op_sel_hi:[1,0,1]
	v_pk_fma_f32 v[2:3], v[18:19], v[74:75], v[2:3] op_sel_hi:[1,0,1]
	v_pk_fma_f32 v[4:5], v[16:17], v[76:77], v[4:5] op_sel_hi:[1,0,1]
	v_pk_fma_f32 v[6:7], v[18:19], v[76:77], v[6:7] op_sel_hi:[1,0,1]
	v_pk_mul_f32 v[60:61], v[0:1], v[24:25]
	v_pk_mul_f32 v[62:63], v[4:5], v[24:25]
	v_pk_fma_f32 v[60:61], v[2:3], v[26:27], v[60:61]
	v_pk_fma_f32 v[62:63], v[6:7], v[26:27], v[62:63]
	v_add_f32_e32 v108, v60, v61
	v_add_f32_e32 v124, v62, v63
	s_waitcnt lgkmcnt(0)
; DEV void scan_tile(const Params& p, int l, int tile, char* smem) {
;     ...
;       auto ldops = [&](ScanOps& o, int sl) {
;         const f32x4* b4 = (const f32x4*)(cb + sl * 384);
;         o.nkk0 = b4[cg * 2]; o.nkk1 = b4[cg * 2 + 1];
;         o.w0 = b4[16 + cg * 2]; o.w1 = b4[16 + cg * 2 + 1];
;         o.kka0 = b4[32 + cg * 2]; o.kka1 = b4[32 + cg * 2 + 1];
;         o.kd0 = b4[48 + cg * 2]; o.kd1 = b4[48 + cg * 2 + 1];
;         o.r0 = b4[64 + cg * 2]; o.r1 = b4[64 + cg * 2 + 1];
;         o.v = cb[sl * 384 + vo];
;       };
;       float ykeep = 0.f;
;       auto step = [&](const ScanOps& o, int sl) {
;         const f32x4 sA = S0 * o.nkk0 + S1 * o.nkk1;
;         const float sa = red8((sA[0] + sA[1]) + (sA[2] + sA[3]));
;         S0 = S0 * o.w0 + (o.kka0 * sa + o.kd0 * o.v);
;         S1 = S1 * o.w1 + (o.kka1 * sa + o.kd1 * o.v);
;         const f32x4 yA = S0 * o.r0 + S1 * o.r1;
;         const float y = red8((yA[0] + yA[1]) + (yA[2] + yA[3]));
	ds_read_b128 v[8:11], v78 offset:18432
	ds_read_b128 v[12:15], v78 offset:18688
	ds_read_b128 v[16:19], v78 offset:18944
	ds_read_b128 v[20:23], v78 offset:19200
	ds_read_b128 v[24:27], v78 offset:19456
	ds_read2st64_b32 v[48:49], v79 offset0:77 offset1:83
	ds_read2st64_b32 v[52:53], v81 offset0:77 offset1:83
	v_pk_mul_f32 v[56:57], v[0:1], v[28:29]
	v_pk_mul_f32 v[58:59], v[4:5], v[28:29]
	v_pk_mul_f32 v[64:65], v[40:41], v[50:51] op_sel:[0,1] op_sel_hi:[1,1]
	v_pk_mul_f32 v[68:69], v[40:41], v[54:55] op_sel:[0,1] op_sel_hi:[1,1]
	v_pk_fma_f32 v[56:57], v[2:3], v[30:31], v[56:57]
	v_pk_fma_f32 v[58:59], v[6:7], v[30:31], v[58:59]
	v_pk_mul_f32 v[66:67], v[42:43], v[50:51] op_sel:[0,1] op_sel_hi:[1,1]
	v_pk_mul_f32 v[70:71], v[42:43], v[54:55] op_sel:[0,1] op_sel_hi:[1,1]
	v_add_f32_e32 v72, v56, v57
	v_add_f32_e32 v73, v58, v59
	v_pk_fma_f32 v[0:1], v[0:1], v[32:33], v[64:65]
	v_add_f32_dpp v72, v72, v72 quad_perm:[1,0,3,2] row_mask:0xf bank_mask:0xf bound_ctrl:1
	v_add_f32_dpp v73, v73, v73 quad_perm:[1,0,3,2] row_mask:0xf bank_mask:0xf bound_ctrl:1
	v_pk_fma_f32 v[4:5], v[4:5], v[32:33], v[68:69]
	v_add_f32_dpp v72, v72, v72 quad_perm:[2,3,0,1] row_mask:0xf bank_mask:0xf bound_ctrl:1
	v_add_f32_dpp v73, v73, v73 quad_perm:[2,3,0,1] row_mask:0xf bank_mask:0xf bound_ctrl:1
	v_pk_fma_f32 v[2:3], v[2:3], v[34:35], v[66:67]
	v_add_f32_dpp v72, v72, v72 row_half_mirror row_mask:0xf bank_mask:0xf bound_ctrl:1
	v_add_f32_dpp v73, v73, v73 row_half_mirror row_mask:0xf bank_mask:0xf bound_ctrl:1
	v_pk_fma_f32 v[6:7], v[6:7], v[34:35], v[70:71]
	v_add_f32_dpp v74, v72, v72 row_mirror row_mask:0xf bank_mask:0xf bound_ctrl:1
	v_add_f32_dpp v76, v73, v73 row_mirror row_mask:0xf bank_mask:0xf bound_ctrl:1
	v_pk_fma_f32 v[0:1], v[36:37], v[74:75], v[0:1] op_sel_hi:[1,0,1]
	v_pk_fma_f32 v[2:3], v[38:39], v[74:75], v[2:3] op_sel_hi:[1,0,1]
	v_pk_fma_f32 v[4:5], v[36:37], v[76:77], v[4:5] op_sel_hi:[1,0,1]
	v_pk_fma_f32 v[6:7], v[38:39], v[76:77], v[6:7] op_sel_hi:[1,0,1]
	v_pk_mul_f32 v[60:61], v[0:1], v[44:45]
	v_pk_mul_f32 v[62:63], v[4:5], v[44:45]
	v_pk_fma_f32 v[60:61], v[2:3], v[46:47], v[60:61]
	v_pk_fma_f32 v[62:63], v[6:7], v[46:47], v[62:63]
	v_add_f32_e32 v109, v60, v61
	v_add_f32_e32 v125, v62, v63
	s_waitcnt lgkmcnt(0)
	ds_read_b128 v[28:31], v78 offset:19968
	ds_read_b128 v[32:35], v78 offset:20224
	ds_read_b128 v[36:39], v78 offset:20480
	ds_read_b128 v[40:43], v78 offset:20736
	ds_read_b128 v[44:47], v78 offset:20992
	v_pk_mul_f32 v[56:57], v[0:1], v[8:9]
	v_pk_mul_f32 v[58:59], v[4:5], v[8:9]
	v_pk_mul_f32 v[64:65], v[20:21], v[48:49] op_sel_hi:[1,0]
	v_pk_mul_f32 v[68:69], v[20:21], v[52:53] op_sel_hi:[1,0]
	v_pk_fma_f32 v[56:57], v[2:3], v[10:11], v[56:57]
	v_pk_fma_f32 v[58:59], v[6:7], v[10:11], v[58:59]
	v_pk_mul_f32 v[66:67], v[22:23], v[48:49] op_sel_hi:[1,0]
	v_pk_mul_f32 v[70:71], v[22:23], v[52:53] op_sel_hi:[1,0]
	v_add_f32_e32 v72, v56, v57
	v_add_f32_e32 v73, v58, v59
	v_pk_fma_f32 v[0:1], v[0:1], v[12:13], v[64:65]
	v_add_f32_dpp v72, v72, v72 quad_perm:[1,0,3,2] row_mask:0xf bank_mask:0xf bound_ctrl:1
	v_add_f32_dpp v73, v73, v73 quad_perm:[1,0,3,2] row_mask:0xf bank_mask:0xf bound_ctrl:1
	v_pk_fma_f32 v[4:5], v[4:5], v[12:13], v[68:69]
	v_add_f32_dpp v72, v72, v72 quad_perm:[2,3,0,1] row_mask:0xf bank_mask:0xf bound_ctrl:1
	v_add_f32_dpp v73, v73, v73 quad_perm:[2,3,0,1] row_mask:0xf bank_mask:0xf bound_ctrl:1
	v_pk_fma_f32 v[2:3], v[2:3], v[14:15], v[66:67]
	v_add_f32_dpp v72, v72, v72 row_half_mirror row_mask:0xf bank_mask:0xf bound_ctrl:1
	v_add_f32_dpp v73, v73, v73 row_half_mirror row_mask:0xf bank_mask:0xf bound_ctrl:1
	v_pk_fma_f32 v[6:7], v[6:7], v[14:15], v[70:71]
	v_add_f32_dpp v74, v72, v72 row_mirror row_mask:0xf bank_mask:0xf bound_ctrl:1
	v_add_f32_dpp v76, v73, v73 row_mirror row_mask:0xf bank_mask:0xf bound_ctrl:1
	v_pk_fma_f32 v[0:1], v[16:17], v[74:75], v[0:1] op_sel_hi:[1,0,1]
	v_pk_fma_f32 v[2:3], v[18:19], v[74:75], v[2:3] op_sel_hi:[1,0,1]
	v_pk_fma_f32 v[4:5], v[16:17], v[76:77], v[4:5] op_sel_hi:[1,0,1]
	v_pk_fma_f32 v[6:7], v[18:19], v[76:77], v[6:7] op_sel_hi:[1,0,1]
	v_pk_mul_f32 v[60:61], v[0:1], v[24:25]
	v_pk_mul_f32 v[62:63], v[4:5], v[24:25]
	v_pk_fma_f32 v[60:61], v[2:3], v[26:27], v[60:61]
	v_pk_fma_f32 v[62:63], v[6:7], v[26:27], v[62:63]
	v_add_f32_e32 v110, v60, v61
	v_add_f32_e32 v126, v62, v63
	s_waitcnt lgkmcnt(0)
	ds_read_b128 v[8:11], v78 offset:21504
	ds_read_b128 v[12:15], v78 offset:21760
	ds_read_b128 v[16:19], v78 offset:22016
	ds_read_b128 v[20:23], v78 offset:22272
	ds_read_b128 v[24:27], v78 offset:22528
	ds_read2st64_b32 v[50:51], v79 offset0:89 offset1:95
	ds_read2st64_b32 v[54:55], v81 offset0:89 offset1:95
	v_pk_mul_f32 v[56:57], v[0:1], v[28:29]
	v_pk_mul_f32 v[58:59], v[4:5], v[28:29]
	v_pk_mul_f32 v[64:65], v[40:41], v[48:49] op_sel:[0,1] op_sel_hi:[1,1]
	v_pk_mul_f32 v[68:69], v[40:41], v[52:53] op_sel:[0,1] op_sel_hi:[1,1]
	v_pk_fma_f32 v[56:57], v[2:3], v[30:31], v[56:57]
	v_pk_fma_f32 v[58:59], v[6:7], v[30:31], v[58:59]
	v_pk_mul_f32 v[66:67], v[42:43], v[48:49] op_sel:[0,1] op_sel_hi:[1,1]
	v_pk_mul_f32 v[70:71], v[42:43], v[52:53] op_sel:[0,1] op_sel_hi:[1,1]
	v_add_f32_e32 v72, v56, v57
	v_add_f32_e32 v73, v58, v59
	v_pk_fma_f32 v[0:1], v[0:1], v[32:33], v[64:65]
	v_add_f32_dpp v72, v72, v72 quad_perm:[1,0,3,2] row_mask:0xf bank_mask:0xf bound_ctrl:1
	v_add_f32_dpp v73, v73, v73 quad_perm:[1,0,3,2] row_mask:0xf bank_mask:0xf bound_ctrl:1
	v_pk_fma_f32 v[4:5], v[4:5], v[32:33], v[68:69]
	v_add_f32_dpp v72, v72, v72 quad_perm:[2,3,0,1] row_mask:0xf bank_mask:0xf bound_ctrl:1
	v_add_f32_dpp v73, v73, v73 quad_perm:[2,3,0,1] row_mask:0xf bank_mask:0xf bound_ctrl:1
	v_pk_fma_f32 v[2:3], v[2:3], v[34:35], v[66:67]
	v_add_f32_dpp v72, v72, v72 row_half_mirror row_mask:0xf bank_mask:0xf bound_ctrl:1
	v_add_f32_dpp v73, v73, v73 row_half_mirror row_mask:0xf bank_mask:0xf bound_ctrl:1
	v_pk_fma_f32 v[6:7], v[6:7], v[34:35], v[70:71]
	v_add_f32_dpp v74, v72, v72 row_mirror row_mask:0xf bank_mask:0xf bound_ctrl:1
	v_add_f32_dpp v76, v73, v73 row_mirror row_mask:0xf bank_mask:0xf bound_ctrl:1
	v_pk_fma_f32 v[0:1], v[36:37], v[74:75], v[0:1] op_sel_hi:[1,0,1]
	v_pk_fma_f32 v[2:3], v[38:39], v[74:75], v[2:3] op_sel_hi:[1,0,1]
	v_pk_fma_f32 v[4:5], v[36:37], v[76:77], v[4:5] op_sel_hi:[1,0,1]
	v_pk_fma_f32 v[6:7], v[38:39], v[76:77], v[6:7] op_sel_hi:[1,0,1]
	v_pk_mul_f32 v[60:61], v[0:1], v[44:45]
	v_pk_mul_f32 v[62:63], v[4:5], v[44:45]
	v_pk_fma_f32 v[60:61], v[2:3], v[46:47], v[60:61]
	v_pk_fma_f32 v[62:63], v[6:7], v[46:47], v[62:63]
	v_add_f32_e32 v111, v60, v61
	v_add_f32_e32 v127, v62, v63
	s_waitcnt lgkmcnt(0)
; DEV void scan_tile(const Params& p, int l, int tile, char* smem) {
;     ...
;       auto ldops = [&](ScanOps& o, int sl) {
;         const f32x4* b4 = (const f32x4*)(cb + sl * 384);
;         o.nkk0 = b4[cg * 2]; o.nkk1 = b4[cg * 2 + 1];
;         o.w0 = b4[16 + cg * 2]; o.w1 = b4[16 + cg * 2 + 1];
;         o.kka0 = b4[32 + cg * 2]; o.kka1 = b4[32 + cg * 2 + 1];
;         o.kd0 = b4[48 + cg * 2]; o.kd1 = b4[48 + cg * 2 + 1];
;         o.r0 = b4[64 + cg * 2]; o.r1 = b4[64 + cg * 2 + 1];
;         o.v = cb[sl * 384 + vo];
;       };
;       float ykeep = 0.f;
;       auto step = [&](const ScanOps& o, int sl) {
;         const f32x4 sA = S0 * o.nkk0 + S1 * o.nkk1;
;         const float sa = red8((sA[0] + sA[1]) + (sA[2] + sA[3]));
;         S0 = S0 * o.w0 + (o.kka0 * sa + o.kd0 * o.v);
;         S1 = S1 * o.w1 + (o.kka1 * sa + o.kd1 * o.v);
;         const f32x4 yA = S0 * o.r0 + S1 * o.r1;
;         const float y = red8((yA[0] + yA[1]) + (yA[2] + yA[3]));
;         ykeep = (cg == (sl & 7)) ? y : ykeep;
;       };
;       ScanOps oa, ob;
;       ldops(oa, 0);
; #pragma unroll
;       for (int s8 = 0; s8 < 32; s8 += 8) {
; #pragma unroll
;         for (int q = 0; q < 8; q += 2) {
;           ldops(ob, s8 + q + 1);
;           step(oa, s8 + q);
;           ldops(oa, (s8 + q + 2) & 31);
;           step(ob, s8 + q + 1);
;         }
;         yw[s8 * 32] = ykeep;
	ds_read_b128 v[28:31], v78 offset:23040
	ds_read_b128 v[32:35], v78 offset:23296
	ds_read_b128 v[36:39], v78 offset:23552
	ds_read_b128 v[40:43], v78 offset:23808
	ds_read_b128 v[44:47], v78 offset:24064
	v_pk_mul_f32 v[56:57], v[0:1], v[8:9]
	v_pk_mul_f32 v[58:59], v[4:5], v[8:9]
	v_pk_mul_f32 v[64:65], v[20:21], v[50:51] op_sel_hi:[1,0]
	v_pk_mul_f32 v[68:69], v[20:21], v[54:55] op_sel_hi:[1,0]
	v_pk_fma_f32 v[56:57], v[2:3], v[10:11], v[56:57]
	v_pk_fma_f32 v[58:59], v[6:7], v[10:11], v[58:59]
	v_pk_mul_f32 v[66:67], v[22:23], v[50:51] op_sel_hi:[1,0]
	v_pk_mul_f32 v[70:71], v[22:23], v[54:55] op_sel_hi:[1,0]
	v_add_f32_e32 v72, v56, v57
	v_add_f32_e32 v73, v58, v59
	v_pk_fma_f32 v[0:1], v[0:1], v[12:13], v[64:65]
	v_add_f32_dpp v72, v72, v72 quad_perm:[1,0,3,2] row_mask:0xf bank_mask:0xf bound_ctrl:1
	v_add_f32_dpp v73, v73, v73 quad_perm:[1,0,3,2] row_mask:0xf bank_mask:0xf bound_ctrl:1
	v_pk_fma_f32 v[4:5], v[4:5], v[12:13], v[68:69]
	v_add_f32_dpp v72, v72, v72 quad_perm:[2,3,0,1] row_mask:0xf bank_mask:0xf bound_ctrl:1
	v_add_f32_dpp v73, v73, v73 quad_perm:[2,3,0,1] row_mask:0xf bank_mask:0xf bound_ctrl:1
	v_pk_fma_f32 v[2:3], v[2:3], v[14:15], v[66:67]
	v_add_f32_dpp v72, v72, v72 row_half_mirror row_mask:0xf bank_mask:0xf bound_ctrl:1
	v_add_f32_dpp v73, v73, v73 row_half_mirror row_mask:0xf bank_mask:0xf bound_ctrl:1
	v_pk_fma_f32 v[6:7], v[6:7], v[14:15], v[70:71]
	v_add_f32_dpp v74, v72, v72 row_mirror row_mask:0xf bank_mask:0xf bound_ctrl:1
	v_add_f32_dpp v76, v73, v73 row_mirror row_mask:0xf bank_mask:0xf bound_ctrl:1
	v_pk_fma_f32 v[0:1], v[16:17], v[74:75], v[0:1] op_sel_hi:[1,0,1]
	v_pk_fma_f32 v[2:3], v[18:19], v[74:75], v[2:3] op_sel_hi:[1,0,1]
	v_pk_fma_f32 v[4:5], v[16:17], v[76:77], v[4:5] op_sel_hi:[1,0,1]
	v_pk_fma_f32 v[6:7], v[18:19], v[76:77], v[6:7] op_sel_hi:[1,0,1]
	v_pk_mul_f32 v[60:61], v[0:1], v[24:25]
	v_pk_mul_f32 v[62:63], v[4:5], v[24:25]
	v_pk_fma_f32 v[60:61], v[2:3], v[26:27], v[60:61]
	v_pk_fma_f32 v[62:63], v[6:7], v[26:27], v[62:63]
	v_add_f32_e32 v112, v60, v61
	v_add_f32_e32 v94, v62, v63
	s_waitcnt lgkmcnt(0)
	ds_read_b128 v[8:11], v78 offset:24576
	ds_read_b128 v[12:15], v78 offset:24832
	ds_read_b128 v[16:19], v78 offset:25088
	ds_read_b128 v[20:23], v78 offset:25344
	ds_read_b128 v[24:27], v78 offset:25600
	ds_read2st64_b32 v[48:49], v79 offset0:101 offset1:107
	ds_read2st64_b32 v[52:53], v81 offset0:101 offset1:107
	v_pk_mul_f32 v[56:57], v[0:1], v[28:29]
	v_pk_mul_f32 v[58:59], v[4:5], v[28:29]
	v_pk_mul_f32 v[64:65], v[40:41], v[50:51] op_sel:[0,1] op_sel_hi:[1,1]
	v_pk_mul_f32 v[68:69], v[40:41], v[54:55] op_sel:[0,1] op_sel_hi:[1,1]
	v_pk_fma_f32 v[56:57], v[2:3], v[30:31], v[56:57]
	v_pk_fma_f32 v[58:59], v[6:7], v[30:31], v[58:59]
	v_pk_mul_f32 v[66:67], v[42:43], v[50:51] op_sel:[0,1] op_sel_hi:[1,1]
	v_pk_mul_f32 v[70:71], v[42:43], v[54:55] op_sel:[0,1] op_sel_hi:[1,1]
	v_add_f32_e32 v72, v56, v57
	v_add_f32_e32 v73, v58, v59
	v_pk_fma_f32 v[0:1], v[0:1], v[32:33], v[64:65]
	v_add_f32_dpp v72, v72, v72 quad_perm:[1,0,3,2] row_mask:0xf bank_mask:0xf bound_ctrl:1
	v_add_f32_dpp v73, v73, v73 quad_perm:[1,0,3,2] row_mask:0xf bank_mask:0xf bound_ctrl:1
	v_pk_fma_f32 v[4:5], v[4:5], v[32:33], v[68:69]
	v_add_f32_dpp v72, v72, v72 quad_perm:[2,3,0,1] row_mask:0xf bank_mask:0xf bound_ctrl:1
	v_add_f32_dpp v73, v73, v73 quad_perm:[2,3,0,1] row_mask:0xf bank_mask:0xf bound_ctrl:1
	v_pk_fma_f32 v[2:3], v[2:3], v[34:35], v[66:67]
	v_add_f32_dpp v72, v72, v72 row_half_mirror row_mask:0xf bank_mask:0xf bound_ctrl:1
	v_add_f32_dpp v73, v73, v73 row_half_mirror row_mask:0xf bank_mask:0xf bound_ctrl:1
	v_pk_fma_f32 v[6:7], v[6:7], v[34:35], v[70:71]
	v_add_f32_dpp v74, v72, v72 row_mirror row_mask:0xf bank_mask:0xf bound_ctrl:1
	v_add_f32_dpp v76, v73, v73 row_mirror row_mask:0xf bank_mask:0xf bound_ctrl:1
	v_pk_fma_f32 v[0:1], v[36:37], v[74:75], v[0:1] op_sel_hi:[1,0,1]
	v_pk_fma_f32 v[2:3], v[38:39], v[74:75], v[2:3] op_sel_hi:[1,0,1]
	v_pk_fma_f32 v[4:5], v[36:37], v[76:77], v[4:5] op_sel_hi:[1,0,1]
	v_pk_fma_f32 v[6:7], v[38:39], v[76:77], v[6:7] op_sel_hi:[1,0,1]
	v_pk_mul_f32 v[60:61], v[0:1], v[44:45]
	v_pk_mul_f32 v[62:63], v[4:5], v[44:45]
	v_pk_fma_f32 v[60:61], v[2:3], v[46:47], v[60:61]
	v_pk_fma_f32 v[62:63], v[6:7], v[46:47], v[62:63]
	v_add_f32_e32 v113, v60, v61
	v_add_f32_e32 v95, v62, v63
	v_add_f32_dpp v98, v98, v98 row_mirror row_mask:0xf bank_mask:0x3 bound_ctrl:1
	v_add_f32_dpp v98, v106, v106 row_mirror row_mask:0xf bank_mask:0xc bound_ctrl:1
	v_add_f32_dpp v99, v99, v99 row_mirror row_mask:0xf bank_mask:0x3 bound_ctrl:1
	v_add_f32_dpp v99, v107, v107 row_mirror row_mask:0xf bank_mask:0xc bound_ctrl:1
	v_add_f32_dpp v100, v100, v100 row_mirror row_mask:0xf bank_mask:0x3 bound_ctrl:1
	v_add_f32_dpp v100, v108, v108 row_mirror row_mask:0xf bank_mask:0xc bound_ctrl:1
	v_add_f32_dpp v101, v101, v101 row_mirror row_mask:0xf bank_mask:0x3 bound_ctrl:1
	v_add_f32_dpp v101, v109, v109 row_mirror row_mask:0xf bank_mask:0xc bound_ctrl:1
	v_add_f32_dpp v102, v102, v102 row_mirror row_mask:0xf bank_mask:0x3 bound_ctrl:1
	v_add_f32_dpp v102, v110, v110 row_mirror row_mask:0xf bank_mask:0xc bound_ctrl:1
	v_add_f32_dpp v103, v103, v103 row_mirror row_mask:0xf bank_mask:0x3 bound_ctrl:1
	v_add_f32_dpp v103, v111, v111 row_mirror row_mask:0xf bank_mask:0xc bound_ctrl:1
	v_add_f32_dpp v104, v104, v104 row_mirror row_mask:0xf bank_mask:0x3 bound_ctrl:1
	v_add_f32_dpp v104, v112, v112 row_mirror row_mask:0xf bank_mask:0xc bound_ctrl:1
	v_add_f32_dpp v105, v105, v105 row_mirror row_mask:0xf bank_mask:0x3 bound_ctrl:1
	v_add_f32_dpp v105, v113, v113 row_mirror row_mask:0xf bank_mask:0xc bound_ctrl:1
; DEV void scan_tile(const Params& p, int l, int tile, char* smem) {
;     ...
;       auto step = [&](const ScanOps& o, int sl) {
;         const f32x4 sA = S0 * o.nkk0 + S1 * o.nkk1;
;         const float sa = red8((sA[0] + sA[1]) + (sA[2] + sA[3]));
;         S0 = S0 * o.w0 + (o.kka0 * sa + o.kd0 * o.v);
;         S1 = S1 * o.w1 + (o.kka1 * sa + o.kd1 * o.v);
;         const f32x4 yA = S0 * o.r0 + S1 * o.r1;
;         const float y = red8((yA[0] + yA[1]) + (yA[2] + yA[3]));
;         ykeep = (cg == (sl & 7)) ? y : ykeep;
;       };
;       ScanOps oa, ob;
;       ldops(oa, 0);
; #pragma unroll
;       for (int s8 = 0; s8 < 32; s8 += 8) {
; #pragma unroll
;         for (int q = 0; q < 8; q += 2) {
;           ldops(ob, s8 + q + 1);
;           step(oa, s8 + q);
;           ldops(oa, (s8 + q + 2) & 31);
;           step(ob, s8 + q + 1);
;         }
;         yw[s8 * 32] = ykeep;
	v_add_f32_dpp v98, v98, v98 row_half_mirror row_mask:0xf bank_mask:0x5 bound_ctrl:1
	v_add_f32_dpp v98, v102, v102 row_half_mirror row_mask:0xf bank_mask:0xa bound_ctrl:1
	v_add_f32_dpp v99, v99, v99 row_half_mirror row_mask:0xf bank_mask:0x5 bound_ctrl:1
	v_add_f32_dpp v99, v103, v103 row_half_mirror row_mask:0xf bank_mask:0xa bound_ctrl:1
	v_add_f32_dpp v100, v100, v100 row_half_mirror row_mask:0xf bank_mask:0x5 bound_ctrl:1
	v_add_f32_dpp v100, v104, v104 row_half_mirror row_mask:0xf bank_mask:0xa bound_ctrl:1
	v_add_f32_dpp v101, v101, v101 row_half_mirror row_mask:0xf bank_mask:0x5 bound_ctrl:1
	v_add_f32_dpp v101, v105, v105 row_half_mirror row_mask:0xf bank_mask:0xa bound_ctrl:1
	v_add_f32_dpp v98, v98, v98 quad_perm:[2,3,0,1] row_mask:0xf bank_mask:0xf bound_ctrl:1
	v_add_f32_dpp v99, v99, v99 quad_perm:[2,3,0,1] row_mask:0xf bank_mask:0xf bound_ctrl:1
	v_add_f32_dpp v100, v100, v100 quad_perm:[2,3,0,1] row_mask:0xf bank_mask:0xf bound_ctrl:1
	v_add_f32_dpp v101, v101, v101 quad_perm:[2,3,0,1] row_mask:0xf bank_mask:0xf bound_ctrl:1
	v_cndmask_b32_e64 v102, v100, v98, s[62:63]
	v_cndmask_b32_e64 v103, v101, v99, s[62:63]
	s_nop 0
	v_add_f32_dpp v102, v102, v102 quad_perm:[1,0,3,2] row_mask:0xf bank_mask:0xf bound_ctrl:1
	v_add_f32_dpp v103, v103, v103 quad_perm:[1,0,3,2] row_mask:0xf bank_mask:0xf bound_ctrl:1
	v_cndmask_b32_e64 v104, v103, v102, s[64:65]
	ds_write_b32 v80, v104 offset:0
	v_add_f32_dpp v114, v114, v114 row_mirror row_mask:0xf bank_mask:0x3 bound_ctrl:1
	v_add_f32_dpp v114, v122, v122 row_mirror row_mask:0xf bank_mask:0xc bound_ctrl:1
	v_add_f32_dpp v115, v115, v115 row_mirror row_mask:0xf bank_mask:0x3 bound_ctrl:1
	v_add_f32_dpp v115, v123, v123 row_mirror row_mask:0xf bank_mask:0xc bound_ctrl:1
	v_add_f32_dpp v116, v116, v116 row_mirror row_mask:0xf bank_mask:0x3 bound_ctrl:1
	v_add_f32_dpp v116, v124, v124 row_mirror row_mask:0xf bank_mask:0xc bound_ctrl:1
	v_add_f32_dpp v117, v117, v117 row_mirror row_mask:0xf bank_mask:0x3 bound_ctrl:1
	v_add_f32_dpp v117, v125, v125 row_mirror row_mask:0xf bank_mask:0xc bound_ctrl:1
	v_add_f32_dpp v118, v118, v118 row_mirror row_mask:0xf bank_mask:0x3 bound_ctrl:1
	v_add_f32_dpp v118, v126, v126 row_mirror row_mask:0xf bank_mask:0xc bound_ctrl:1
	v_add_f32_dpp v119, v119, v119 row_mirror row_mask:0xf bank_mask:0x3 bound_ctrl:1
	v_add_f32_dpp v119, v127, v127 row_mirror row_mask:0xf bank_mask:0xc bound_ctrl:1
	v_add_f32_dpp v120, v120, v120 row_mirror row_mask:0xf bank_mask:0x3 bound_ctrl:1
	v_add_f32_dpp v120, v94, v94 row_mirror row_mask:0xf bank_mask:0xc bound_ctrl:1
	v_add_f32_dpp v121, v121, v121 row_mirror row_mask:0xf bank_mask:0x3 bound_ctrl:1
	v_add_f32_dpp v121, v95, v95 row_mirror row_mask:0xf bank_mask:0xc bound_ctrl:1
	v_add_f32_dpp v114, v114, v114 row_half_mirror row_mask:0xf bank_mask:0x5 bound_ctrl:1
	v_add_f32_dpp v114, v118, v118 row_half_mirror row_mask:0xf bank_mask:0xa bound_ctrl:1
	v_add_f32_dpp v115, v115, v115 row_half_mirror row_mask:0xf bank_mask:0x5 bound_ctrl:1
	v_add_f32_dpp v115, v119, v119 row_half_mirror row_mask:0xf bank_mask:0xa bound_ctrl:1
	v_add_f32_dpp v116, v116, v116 row_half_mirror row_mask:0xf bank_mask:0x5 bound_ctrl:1
	v_add_f32_dpp v116, v120, v120 row_half_mirror row_mask:0xf bank_mask:0xa bound_ctrl:1
	v_add_f32_dpp v117, v117, v117 row_half_mirror row_mask:0xf bank_mask:0x5 bound_ctrl:1
	v_add_f32_dpp v117, v121, v121 row_half_mirror row_mask:0xf bank_mask:0xa bound_ctrl:1
	v_add_f32_dpp v114, v114, v114 quad_perm:[2,3,0,1] row_mask:0xf bank_mask:0xf bound_ctrl:1
	v_add_f32_dpp v115, v115, v115 quad_perm:[2,3,0,1] row_mask:0xf bank_mask:0xf bound_ctrl:1
	v_add_f32_dpp v116, v116, v116 quad_perm:[2,3,0,1] row_mask:0xf bank_mask:0xf bound_ctrl:1
	v_add_f32_dpp v117, v117, v117 quad_perm:[2,3,0,1] row_mask:0xf bank_mask:0xf bound_ctrl:1
	v_cndmask_b32_e64 v118, v116, v114, s[62:63]
	v_cndmask_b32_e64 v119, v117, v115, s[62:63]
	s_nop 0
	v_add_f32_dpp v118, v118, v118 quad_perm:[1,0,3,2] row_mask:0xf bank_mask:0xf bound_ctrl:1
	v_add_f32_dpp v119, v119, v119 quad_perm:[1,0,3,2] row_mask:0xf bank_mask:0xf bound_ctrl:1
	v_cndmask_b32_e64 v120, v119, v118, s[64:65]
	ds_write_b32 v82, v120 offset:0
	s_waitcnt lgkmcnt(2)
	ds_read_b128 v[28:31], v78 offset:26112
	ds_read_b128 v[32:35], v78 offset:26368
	ds_read_b128 v[36:39], v78 offset:26624
	ds_read_b128 v[40:43], v78 offset:26880
	ds_read_b128 v[44:47], v78 offset:27136
	v_pk_mul_f32 v[56:57], v[0:1], v[8:9]
	v_pk_mul_f32 v[58:59], v[4:5], v[8:9]
	v_pk_mul_f32 v[64:65], v[20:21], v[48:49] op_sel_hi:[1,0]
	v_pk_mul_f32 v[68:69], v[20:21], v[52:53] op_sel_hi:[1,0]
	v_pk_fma_f32 v[56:57], v[2:3], v[10:11], v[56:57]
	v_pk_fma_f32 v[58:59], v[6:7], v[10:11], v[58:59]
	v_pk_mul_f32 v[66:67], v[22:23], v[48:49] op_sel_hi:[1,0]
	v_pk_mul_f32 v[70:71], v[22:23], v[52:53] op_sel_hi:[1,0]
	v_add_f32_e32 v72, v56, v57
	v_add_f32_e32 v73, v58, v59
	v_pk_fma_f32 v[0:1], v[0:1], v[12:13], v[64:65]
	v_add_f32_dpp v72, v72, v72 quad_perm:[1,0,3,2] row_mask:0xf bank_mask:0xf bound_ctrl:1
	v_add_f32_dpp v73, v73, v73 quad_perm:[1,0,3,2] row_mask:0xf bank_mask:0xf bound_ctrl:1
	v_pk_fma_f32 v[4:5], v[4:5], v[12:13], v[68:69]
	v_add_f32_dpp v72, v72, v72 quad_perm:[2,3,0,1] row_mask:0xf bank_mask:0xf bound_ctrl:1
	v_add_f32_dpp v73, v73, v73 quad_perm:[2,3,0,1] row_mask:0xf bank_mask:0xf bound_ctrl:1
	v_pk_fma_f32 v[2:3], v[2:3], v[14:15], v[66:67]
	v_add_f32_dpp v72, v72, v72 row_half_mirror row_mask:0xf bank_mask:0xf bound_ctrl:1
	v_add_f32_dpp v73, v73, v73 row_half_mirror row_mask:0xf bank_mask:0xf bound_ctrl:1
	v_pk_fma_f32 v[6:7], v[6:7], v[14:15], v[70:71]
	v_add_f32_dpp v74, v72, v72 row_mirror row_mask:0xf bank_mask:0xf bound_ctrl:1
	v_add_f32_dpp v76, v73, v73 row_mirror row_mask:0xf bank_mask:0xf bound_ctrl:1
	v_pk_fma_f32 v[0:1], v[16:17], v[74:75], v[0:1] op_sel_hi:[1,0,1]
	v_pk_fma_f32 v[2:3], v[18:19], v[74:75], v[2:3] op_sel_hi:[1,0,1]
	v_pk_fma_f32 v[4:5], v[16:17], v[76:77], v[4:5] op_sel_hi:[1,0,1]
	v_pk_fma_f32 v[6:7], v[18:19], v[76:77], v[6:7] op_sel_hi:[1,0,1]
	v_pk_mul_f32 v[60:61], v[0:1], v[24:25]
	v_pk_mul_f32 v[62:63], v[4:5], v[24:25]
	v_pk_fma_f32 v[60:61], v[2:3], v[26:27], v[60:61]
	v_pk_fma_f32 v[62:63], v[6:7], v[26:27], v[62:63]
	v_add_f32_e32 v98, v60, v61
	v_add_f32_e32 v114, v62, v63
	s_waitcnt lgkmcnt(0)
; DEV void scan_tile(const Params& p, int l, int tile, char* smem) {
;     ...
;       auto ldops = [&](ScanOps& o, int sl) {
;         const f32x4* b4 = (const f32x4*)(cb + sl * 384);
;         o.nkk0 = b4[cg * 2]; o.nkk1 = b4[cg * 2 + 1];
;         o.w0 = b4[16 + cg * 2]; o.w1 = b4[16 + cg * 2 + 1];
;         o.kka0 = b4[32 + cg * 2]; o.kka1 = b4[32 + cg * 2 + 1];
;         o.kd0 = b4[48 + cg * 2]; o.kd1 = b4[48 + cg * 2 + 1];
;         o.r0 = b4[64 + cg * 2]; o.r1 = b4[64 + cg * 2 + 1];
;         o.v = cb[sl * 384 + vo];
;       };
;       float ykeep = 0.f;
;       auto step = [&](const ScanOps& o, int sl) {
;         const f32x4 sA = S0 * o.nkk0 + S1 * o.nkk1;
;         const float sa = red8((sA[0] + sA[1]) + (sA[2] + sA[3]));
;         S0 = S0 * o.w0 + (o.kka0 * sa + o.kd0 * o.v);
;         S1 = S1 * o.w1 + (o.kka1 * sa + o.kd1 * o.v);
;         const f32x4 yA = S0 * o.r0 + S1 * o.r1;
;         const float y = red8((yA[0] + yA[1]) + (yA[2] + yA[3]));
;         ykeep = (cg == (sl & 7)) ? y : ykeep;
;       };
	ds_read_b128 v[8:11], v78 offset:27648
	ds_read_b128 v[12:15], v78 offset:27904
	ds_read_b128 v[16:19], v78 offset:28160
	ds_read_b128 v[20:23], v78 offset:28416
	ds_read_b128 v[24:27], v78 offset:28672
	ds_read2st64_b32 v[50:51], v79 offset0:113 offset1:119
	ds_read2st64_b32 v[54:55], v81 offset0:113 offset1:119
	v_pk_mul_f32 v[56:57], v[0:1], v[28:29]
	v_pk_mul_f32 v[58:59], v[4:5], v[28:29]
	v_pk_mul_f32 v[64:65], v[40:41], v[48:49] op_sel:[0,1] op_sel_hi:[1,1]
	v_pk_mul_f32 v[68:69], v[40:41], v[52:53] op_sel:[0,1] op_sel_hi:[1,1]
	v_pk_fma_f32 v[56:57], v[2:3], v[30:31], v[56:57]
	v_pk_fma_f32 v[58:59], v[6:7], v[30:31], v[58:59]
	v_pk_mul_f32 v[66:67], v[42:43], v[48:49] op_sel:[0,1] op_sel_hi:[1,1]
	v_pk_mul_f32 v[70:71], v[42:43], v[52:53] op_sel:[0,1] op_sel_hi:[1,1]
	v_add_f32_e32 v72, v56, v57
	v_add_f32_e32 v73, v58, v59
	v_pk_fma_f32 v[0:1], v[0:1], v[32:33], v[64:65]
	v_add_f32_dpp v72, v72, v72 quad_perm:[1,0,3,2] row_mask:0xf bank_mask:0xf bound_ctrl:1
	v_add_f32_dpp v73, v73, v73 quad_perm:[1,0,3,2] row_mask:0xf bank_mask:0xf bound_ctrl:1
	v_pk_fma_f32 v[4:5], v[4:5], v[32:33], v[68:69]
	v_add_f32_dpp v72, v72, v72 quad_perm:[2,3,0,1] row_mask:0xf bank_mask:0xf bound_ctrl:1
	v_add_f32_dpp v73, v73, v73 quad_perm:[2,3,0,1] row_mask:0xf bank_mask:0xf bound_ctrl:1
	v_pk_fma_f32 v[2:3], v[2:3], v[34:35], v[66:67]
	v_add_f32_dpp v72, v72, v72 row_half_mirror row_mask:0xf bank_mask:0xf bound_ctrl:1
	v_add_f32_dpp v73, v73, v73 row_half_mirror row_mask:0xf bank_mask:0xf bound_ctrl:1
	v_pk_fma_f32 v[6:7], v[6:7], v[34:35], v[70:71]
	v_add_f32_dpp v74, v72, v72 row_mirror row_mask:0xf bank_mask:0xf bound_ctrl:1
	v_add_f32_dpp v76, v73, v73 row_mirror row_mask:0xf bank_mask:0xf bound_ctrl:1
	v_pk_fma_f32 v[0:1], v[36:37], v[74:75], v[0:1] op_sel_hi:[1,0,1]
	v_pk_fma_f32 v[2:3], v[38:39], v[74:75], v[2:3] op_sel_hi:[1,0,1]
	v_pk_fma_f32 v[4:5], v[36:37], v[76:77], v[4:5] op_sel_hi:[1,0,1]
	v_pk_fma_f32 v[6:7], v[38:39], v[76:77], v[6:7] op_sel_hi:[1,0,1]
	v_pk_mul_f32 v[60:61], v[0:1], v[44:45]
	v_pk_mul_f32 v[62:63], v[4:5], v[44:45]
	v_pk_fma_f32 v[60:61], v[2:3], v[46:47], v[60:61]
	v_pk_fma_f32 v[62:63], v[6:7], v[46:47], v[62:63]
	v_add_f32_e32 v99, v60, v61
	v_add_f32_e32 v115, v62, v63
	s_waitcnt lgkmcnt(0)
	ds_read_b128 v[28:31], v78 offset:29184
	ds_read_b128 v[32:35], v78 offset:29440
	ds_read_b128 v[36:39], v78 offset:29696
	ds_read_b128 v[40:43], v78 offset:29952
	ds_read_b128 v[44:47], v78 offset:30208
	v_pk_mul_f32 v[56:57], v[0:1], v[8:9]
	v_pk_mul_f32 v[58:59], v[4:5], v[8:9]
	v_pk_mul_f32 v[64:65], v[20:21], v[50:51] op_sel_hi:[1,0]
	v_pk_mul_f32 v[68:69], v[20:21], v[54:55] op_sel_hi:[1,0]
	v_pk_fma_f32 v[56:57], v[2:3], v[10:11], v[56:57]
	v_pk_fma_f32 v[58:59], v[6:7], v[10:11], v[58:59]
	v_pk_mul_f32 v[66:67], v[22:23], v[50:51] op_sel_hi:[1,0]
	v_pk_mul_f32 v[70:71], v[22:23], v[54:55] op_sel_hi:[1,0]
	v_add_f32_e32 v72, v56, v57
	v_add_f32_e32 v73, v58, v59
	v_pk_fma_f32 v[0:1], v[0:1], v[12:13], v[64:65]
	v_add_f32_dpp v72, v72, v72 quad_perm:[1,0,3,2] row_mask:0xf bank_mask:0xf bound_ctrl:1
	v_add_f32_dpp v73, v73, v73 quad_perm:[1,0,3,2] row_mask:0xf bank_mask:0xf bound_ctrl:1
	v_pk_fma_f32 v[4:5], v[4:5], v[12:13], v[68:69]
	v_add_f32_dpp v72, v72, v72 quad_perm:[2,3,0,1] row_mask:0xf bank_mask:0xf bound_ctrl:1
	v_add_f32_dpp v73, v73, v73 quad_perm:[2,3,0,1] row_mask:0xf bank_mask:0xf bound_ctrl:1
	v_pk_fma_f32 v[2:3], v[2:3], v[14:15], v[66:67]
	v_add_f32_dpp v72, v72, v72 row_half_mirror row_mask:0xf bank_mask:0xf bound_ctrl:1
	v_add_f32_dpp v73, v73, v73 row_half_mirror row_mask:0xf bank_mask:0xf bound_ctrl:1
	v_pk_fma_f32 v[6:7], v[6:7], v[14:15], v[70:71]
	v_add_f32_dpp v74, v72, v72 row_mirror row_mask:0xf bank_mask:0xf bound_ctrl:1
	v_add_f32_dpp v76, v73, v73 row_mirror row_mask:0xf bank_mask:0xf bound_ctrl:1
	v_pk_fma_f32 v[0:1], v[16:17], v[74:75], v[0:1] op_sel_hi:[1,0,1]
	v_pk_fma_f32 v[2:3], v[18:19], v[74:75], v[2:3] op_sel_hi:[1,0,1]
	v_pk_fma_f32 v[4:5], v[16:17], v[76:77], v[4:5] op_sel_hi:[1,0,1]
	v_pk_fma_f32 v[6:7], v[18:19], v[76:77], v[6:7] op_sel_hi:[1,0,1]
	v_pk_mul_f32 v[60:61], v[0:1], v[24:25]
	v_pk_mul_f32 v[62:63], v[4:5], v[24:25]
	v_pk_fma_f32 v[60:61], v[2:3], v[26:27], v[60:61]
	v_pk_fma_f32 v[62:63], v[6:7], v[26:27], v[62:63]
	v_add_f32_e32 v100, v60, v61
	v_add_f32_e32 v116, v62, v63
	s_waitcnt lgkmcnt(0)
	ds_read_b128 v[8:11], v78 offset:30720
	ds_read_b128 v[12:15], v78 offset:30976
	ds_read_b128 v[16:19], v78 offset:31232
	ds_read_b128 v[20:23], v78 offset:31488
	ds_read_b128 v[24:27], v78 offset:31744
	ds_read2st64_b32 v[48:49], v79 offset0:125 offset1:131
	ds_read2st64_b32 v[52:53], v81 offset0:125 offset1:131
	v_pk_mul_f32 v[56:57], v[0:1], v[28:29]
	v_pk_mul_f32 v[58:59], v[4:5], v[28:29]
	v_pk_mul_f32 v[64:65], v[40:41], v[50:51] op_sel:[0,1] op_sel_hi:[1,1]
	v_pk_mul_f32 v[68:69], v[40:41], v[54:55] op_sel:[0,1] op_sel_hi:[1,1]
	v_pk_fma_f32 v[56:57], v[2:3], v[30:31], v[56:57]
	v_pk_fma_f32 v[58:59], v[6:7], v[30:31], v[58:59]
	v_pk_mul_f32 v[66:67], v[42:43], v[50:51] op_sel:[0,1] op_sel_hi:[1,1]
	v_pk_mul_f32 v[70:71], v[42:43], v[54:55] op_sel:[0,1] op_sel_hi:[1,1]
	v_add_f32_e32 v72, v56, v57
	v_add_f32_e32 v73, v58, v59
	v_pk_fma_f32 v[0:1], v[0:1], v[32:33], v[64:65]
	v_add_f32_dpp v72, v72, v72 quad_perm:[1,0,3,2] row_mask:0xf bank_mask:0xf bound_ctrl:1
	v_add_f32_dpp v73, v73, v73 quad_perm:[1,0,3,2] row_mask:0xf bank_mask:0xf bound_ctrl:1
	v_pk_fma_f32 v[4:5], v[4:5], v[32:33], v[68:69]
	v_add_f32_dpp v72, v72, v72 quad_perm:[2,3,0,1] row_mask:0xf bank_mask:0xf bound_ctrl:1
	v_add_f32_dpp v73, v73, v73 quad_perm:[2,3,0,1] row_mask:0xf bank_mask:0xf bound_ctrl:1
	v_pk_fma_f32 v[2:3], v[2:3], v[34:35], v[66:67]
	v_add_f32_dpp v72, v72, v72 row_half_mirror row_mask:0xf bank_mask:0xf bound_ctrl:1
	v_add_f32_dpp v73, v73, v73 row_half_mirror row_mask:0xf bank_mask:0xf bound_ctrl:1
	v_pk_fma_f32 v[6:7], v[6:7], v[34:35], v[70:71]
	v_add_f32_dpp v74, v72, v72 row_mirror row_mask:0xf bank_mask:0xf bound_ctrl:1
	v_add_f32_dpp v76, v73, v73 row_mirror row_mask:0xf bank_mask:0xf bound_ctrl:1
	v_pk_fma_f32 v[0:1], v[36:37], v[74:75], v[0:1] op_sel_hi:[1,0,1]
	v_pk_fma_f32 v[2:3], v[38:39], v[74:75], v[2:3] op_sel_hi:[1,0,1]
	v_pk_fma_f32 v[4:5], v[36:37], v[76:77], v[4:5] op_sel_hi:[1,0,1]
	v_pk_fma_f32 v[6:7], v[38:39], v[76:77], v[6:7] op_sel_hi:[1,0,1]
	v_pk_mul_f32 v[60:61], v[0:1], v[44:45]
	v_pk_mul_f32 v[62:63], v[4:5], v[44:45]
	v_pk_fma_f32 v[60:61], v[2:3], v[46:47], v[60:61]
	v_pk_fma_f32 v[62:63], v[6:7], v[46:47], v[62:63]
	v_add_f32_e32 v101, v60, v61
	v_add_f32_e32 v117, v62, v63
	s_waitcnt lgkmcnt(0)
; DEV void scan_tile(const Params& p, int l, int tile, char* smem) {
;     ...
;       auto ldops = [&](ScanOps& o, int sl) {
;         const f32x4* b4 = (const f32x4*)(cb + sl * 384);
;         o.nkk0 = b4[cg * 2]; o.nkk1 = b4[cg * 2 + 1];
;         o.w0 = b4[16 + cg * 2]; o.w1 = b4[16 + cg * 2 + 1];
;         o.kka0 = b4[32 + cg * 2]; o.kka1 = b4[32 + cg * 2 + 1];
;         o.kd0 = b4[48 + cg * 2]; o.kd1 = b4[48 + cg * 2 + 1];
;         o.r0 = b4[64 + cg * 2]; o.r1 = b4[64 + cg * 2 + 1];
;         o.v = cb[sl * 384 + vo];
;       };
;       float ykeep = 0.f;
;       auto step = [&](const ScanOps& o, int sl) {
;         const f32x4 sA = S0 * o.nkk0 + S1 * o.nkk1;
;         const float sa = red8((sA[0] + sA[1]) + (sA[2] + sA[3]));
;         S0 = S0 * o.w0 + (o.kka0 * sa + o.kd0 * o.v);
;         S1 = S1 * o.w1 + (o.kka1 * sa + o.kd1 * o.v);
;         const f32x4 yA = S0 * o.r0 + S1 * o.r1;
;         const float y = red8((yA[0] + yA[1]) + (yA[2] + yA[3]));
;         ykeep = (cg == (sl & 7)) ? y : ykeep;
;       };
	ds_read_b128 v[28:31], v78 offset:32256
	ds_read_b128 v[32:35], v78 offset:32512
	ds_read_b128 v[36:39], v78 offset:32768
	ds_read_b128 v[40:43], v78 offset:33024
	ds_read_b128 v[44:47], v78 offset:33280
	v_pk_mul_f32 v[56:57], v[0:1], v[8:9]
	v_pk_mul_f32 v[58:59], v[4:5], v[8:9]
	v_pk_mul_f32 v[64:65], v[20:21], v[48:49] op_sel_hi:[1,0]
	v_pk_mul_f32 v[68:69], v[20:21], v[52:53] op_sel_hi:[1,0]
	v_pk_fma_f32 v[56:57], v[2:3], v[10:11], v[56:57]
	v_pk_fma_f32 v[58:59], v[6:7], v[10:11], v[58:59]
	v_pk_mul_f32 v[66:67], v[22:23], v[48:49] op_sel_hi:[1,0]
	v_pk_mul_f32 v[70:71], v[22:23], v[52:53] op_sel_hi:[1,0]
	v_add_f32_e32 v72, v56, v57
	v_add_f32_e32 v73, v58, v59
	v_pk_fma_f32 v[0:1], v[0:1], v[12:13], v[64:65]
	v_add_f32_dpp v72, v72, v72 quad_perm:[1,0,3,2] row_mask:0xf bank_mask:0xf bound_ctrl:1
	v_add_f32_dpp v73, v73, v73 quad_perm:[1,0,3,2] row_mask:0xf bank_mask:0xf bound_ctrl:1
	v_pk_fma_f32 v[4:5], v[4:5], v[12:13], v[68:69]
	v_add_f32_dpp v72, v72, v72 quad_perm:[2,3,0,1] row_mask:0xf bank_mask:0xf bound_ctrl:1
	v_add_f32_dpp v73, v73, v73 quad_perm:[2,3,0,1] row_mask:0xf bank_mask:0xf bound_ctrl:1
	v_pk_fma_f32 v[2:3], v[2:3], v[14:15], v[66:67]
	v_add_f32_dpp v72, v72, v72 row_half_mirror row_mask:0xf bank_mask:0xf bound_ctrl:1
	v_add_f32_dpp v73, v73, v73 row_half_mirror row_mask:0xf bank_mask:0xf bound_ctrl:1
	v_pk_fma_f32 v[6:7], v[6:7], v[14:15], v[70:71]
	v_add_f32_dpp v74, v72, v72 row_mirror row_mask:0xf bank_mask:0xf bound_ctrl:1
	v_add_f32_dpp v76, v73, v73 row_mirror row_mask:0xf bank_mask:0xf bound_ctrl:1
	v_pk_fma_f32 v[0:1], v[16:17], v[74:75], v[0:1] op_sel_hi:[1,0,1]
	v_pk_fma_f32 v[2:3], v[18:19], v[74:75], v[2:3] op_sel_hi:[1,0,1]
	v_pk_fma_f32 v[4:5], v[16:17], v[76:77], v[4:5] op_sel_hi:[1,0,1]
	v_pk_fma_f32 v[6:7], v[18:19], v[76:77], v[6:7] op_sel_hi:[1,0,1]
	v_pk_mul_f32 v[60:61], v[0:1], v[24:25]
	v_pk_mul_f32 v[62:63], v[4:5], v[24:25]
	v_pk_fma_f32 v[60:61], v[2:3], v[26:27], v[60:61]
	v_pk_fma_f32 v[62:63], v[6:7], v[26:27], v[62:63]
	v_add_f32_e32 v102, v60, v61
	v_add_f32_e32 v118, v62, v63
	s_waitcnt lgkmcnt(0)
	ds_read_b128 v[8:11], v78 offset:33792
	ds_read_b128 v[12:15], v78 offset:34048
	ds_read_b128 v[16:19], v78 offset:34304
	ds_read_b128 v[20:23], v78 offset:34560
	ds_read_b128 v[24:27], v78 offset:34816
	ds_read2st64_b32 v[50:51], v79 offset0:137 offset1:143
	ds_read2st64_b32 v[54:55], v81 offset0:137 offset1:143
	v_pk_mul_f32 v[56:57], v[0:1], v[28:29]
	v_pk_mul_f32 v[58:59], v[4:5], v[28:29]
	v_pk_mul_f32 v[64:65], v[40:41], v[48:49] op_sel:[0,1] op_sel_hi:[1,1]
	v_pk_mul_f32 v[68:69], v[40:41], v[52:53] op_sel:[0,1] op_sel_hi:[1,1]
	v_pk_fma_f32 v[56:57], v[2:3], v[30:31], v[56:57]
	v_pk_fma_f32 v[58:59], v[6:7], v[30:31], v[58:59]
	v_pk_mul_f32 v[66:67], v[42:43], v[48:49] op_sel:[0,1] op_sel_hi:[1,1]
	v_pk_mul_f32 v[70:71], v[42:43], v[52:53] op_sel:[0,1] op_sel_hi:[1,1]
	v_add_f32_e32 v72, v56, v57
	v_add_f32_e32 v73, v58, v59
	v_pk_fma_f32 v[0:1], v[0:1], v[32:33], v[64:65]
	v_add_f32_dpp v72, v72, v72 quad_perm:[1,0,3,2] row_mask:0xf bank_mask:0xf bound_ctrl:1
	v_add_f32_dpp v73, v73, v73 quad_perm:[1,0,3,2] row_mask:0xf bank_mask:0xf bound_ctrl:1
	v_pk_fma_f32 v[4:5], v[4:5], v[32:33], v[68:69]
	v_add_f32_dpp v72, v72, v72 quad_perm:[2,3,0,1] row_mask:0xf bank_mask:0xf bound_ctrl:1
	v_add_f32_dpp v73, v73, v73 quad_perm:[2,3,0,1] row_mask:0xf bank_mask:0xf bound_ctrl:1
	v_pk_fma_f32 v[2:3], v[2:3], v[34:35], v[66:67]
	v_add_f32_dpp v72, v72, v72 row_half_mirror row_mask:0xf bank_mask:0xf bound_ctrl:1
	v_add_f32_dpp v73, v73, v73 row_half_mirror row_mask:0xf bank_mask:0xf bound_ctrl:1
	v_pk_fma_f32 v[6:7], v[6:7], v[34:35], v[70:71]
	v_add_f32_dpp v74, v72, v72 row_mirror row_mask:0xf bank_mask:0xf bound_ctrl:1
	v_add_f32_dpp v76, v73, v73 row_mirror row_mask:0xf bank_mask:0xf bound_ctrl:1
	v_pk_fma_f32 v[0:1], v[36:37], v[74:75], v[0:1] op_sel_hi:[1,0,1]
	v_pk_fma_f32 v[2:3], v[38:39], v[74:75], v[2:3] op_sel_hi:[1,0,1]
	v_pk_fma_f32 v[4:5], v[36:37], v[76:77], v[4:5] op_sel_hi:[1,0,1]
	v_pk_fma_f32 v[6:7], v[38:39], v[76:77], v[6:7] op_sel_hi:[1,0,1]
	v_pk_mul_f32 v[60:61], v[0:1], v[44:45]
	v_pk_mul_f32 v[62:63], v[4:5], v[44:45]
	v_pk_fma_f32 v[60:61], v[2:3], v[46:47], v[60:61]
	v_pk_fma_f32 v[62:63], v[6:7], v[46:47], v[62:63]
	v_add_f32_e32 v103, v60, v61
	v_add_f32_e32 v119, v62, v63
	s_waitcnt lgkmcnt(0)
	ds_read_b128 v[28:31], v78 offset:35328
	ds_read_b128 v[32:35], v78 offset:35584
	ds_read_b128 v[36:39], v78 offset:35840
	ds_read_b128 v[40:43], v78 offset:36096
	ds_read_b128 v[44:47], v78 offset:36352
	v_pk_mul_f32 v[56:57], v[0:1], v[8:9]
	v_pk_mul_f32 v[58:59], v[4:5], v[8:9]
	v_pk_mul_f32 v[64:65], v[20:21], v[50:51] op_sel_hi:[1,0]
	v_pk_mul_f32 v[68:69], v[20:21], v[54:55] op_sel_hi:[1,0]
	v_pk_fma_f32 v[56:57], v[2:3], v[10:11], v[56:57]
	v_pk_fma_f32 v[58:59], v[6:7], v[10:11], v[58:59]
	v_pk_mul_f32 v[66:67], v[22:23], v[50:51] op_sel_hi:[1,0]
	v_pk_mul_f32 v[70:71], v[22:23], v[54:55] op_sel_hi:[1,0]
	v_add_f32_e32 v72, v56, v57
	v_add_f32_e32 v73, v58, v59
	v_pk_fma_f32 v[0:1], v[0:1], v[12:13], v[64:65]
	v_add_f32_dpp v72, v72, v72 quad_perm:[1,0,3,2] row_mask:0xf bank_mask:0xf bound_ctrl:1
	v_add_f32_dpp v73, v73, v73 quad_perm:[1,0,3,2] row_mask:0xf bank_mask:0xf bound_ctrl:1
	v_pk_fma_f32 v[4:5], v[4:5], v[12:13], v[68:69]
	v_add_f32_dpp v72, v72, v72 quad_perm:[2,3,0,1] row_mask:0xf bank_mask:0xf bound_ctrl:1
	v_add_f32_dpp v73, v73, v73 quad_perm:[2,3,0,1] row_mask:0xf bank_mask:0xf bound_ctrl:1
	v_pk_fma_f32 v[2:3], v[2:3], v[14:15], v[66:67]
	v_add_f32_dpp v72, v72, v72 row_half_mirror row_mask:0xf bank_mask:0xf bound_ctrl:1
	v_add_f32_dpp v73, v73, v73 row_half_mirror row_mask:0xf bank_mask:0xf bound_ctrl:1
	v_pk_fma_f32 v[6:7], v[6:7], v[14:15], v[70:71]
	v_add_f32_dpp v74, v72, v72 row_mirror row_mask:0xf bank_mask:0xf bound_ctrl:1
	v_add_f32_dpp v76, v73, v73 row_mirror row_mask:0xf bank_mask:0xf bound_ctrl:1
	v_pk_fma_f32 v[0:1], v[16:17], v[74:75], v[0:1] op_sel_hi:[1,0,1]
	v_pk_fma_f32 v[2:3], v[18:19], v[74:75], v[2:3] op_sel_hi:[1,0,1]
	v_pk_fma_f32 v[4:5], v[16:17], v[76:77], v[4:5] op_sel_hi:[1,0,1]
	v_pk_fma_f32 v[6:7], v[18:19], v[76:77], v[6:7] op_sel_hi:[1,0,1]
	v_pk_mul_f32 v[60:61], v[0:1], v[24:25]
	v_pk_mul_f32 v[62:63], v[4:5], v[24:25]
	v_pk_fma_f32 v[60:61], v[2:3], v[26:27], v[60:61]
	v_pk_fma_f32 v[62:63], v[6:7], v[26:27], v[62:63]
	v_add_f32_e32 v104, v60, v61
	v_add_f32_e32 v120, v62, v63
	s_waitcnt lgkmcnt(0)
; DEV void scan_tile(const Params& p, int l, int tile, char* smem) {
;     ...
;       auto ldops = [&](ScanOps& o, int sl) {
;         const f32x4* b4 = (const f32x4*)(cb + sl * 384);
;         o.nkk0 = b4[cg * 2]; o.nkk1 = b4[cg * 2 + 1];
;         o.w0 = b4[16 + cg * 2]; o.w1 = b4[16 + cg * 2 + 1];
;         o.kka0 = b4[32 + cg * 2]; o.kka1 = b4[32 + cg * 2 + 1];
;         o.kd0 = b4[48 + cg * 2]; o.kd1 = b4[48 + cg * 2 + 1];
;         o.r0 = b4[64 + cg * 2]; o.r1 = b4[64 + cg * 2 + 1];
;         o.v = cb[sl * 384 + vo];
;       };
;       float ykeep = 0.f;
;       auto step = [&](const ScanOps& o, int sl) {
;         const f32x4 sA = S0 * o.nkk0 + S1 * o.nkk1;
;         const float sa = red8((sA[0] + sA[1]) + (sA[2] + sA[3]));
;         S0 = S0 * o.w0 + (o.kka0 * sa + o.kd0 * o.v);
;         S1 = S1 * o.w1 + (o.kka1 * sa + o.kd1 * o.v);
;         const f32x4 yA = S0 * o.r0 + S1 * o.r1;
;         const float y = red8((yA[0] + yA[1]) + (yA[2] + yA[3]));
;         ykeep = (cg == (sl & 7)) ? y : ykeep;
;       };
	ds_read_b128 v[8:11], v78 offset:36864
	ds_read_b128 v[12:15], v78 offset:37120
	ds_read_b128 v[16:19], v78 offset:37376
	ds_read_b128 v[20:23], v78 offset:37632
	ds_read_b128 v[24:27], v78 offset:37888
	ds_read2st64_b32 v[48:49], v79 offset0:149 offset1:155
	ds_read2st64_b32 v[52:53], v81 offset0:149 offset1:155
	v_pk_mul_f32 v[56:57], v[0:1], v[28:29]
	v_pk_mul_f32 v[58:59], v[4:5], v[28:29]
	v_pk_mul_f32 v[64:65], v[40:41], v[50:51] op_sel:[0,1] op_sel_hi:[1,1]
	v_pk_mul_f32 v[68:69], v[40:41], v[54:55] op_sel:[0,1] op_sel_hi:[1,1]
	v_pk_fma_f32 v[56:57], v[2:3], v[30:31], v[56:57]
	v_pk_fma_f32 v[58:59], v[6:7], v[30:31], v[58:59]
	v_pk_mul_f32 v[66:67], v[42:43], v[50:51] op_sel:[0,1] op_sel_hi:[1,1]
	v_pk_mul_f32 v[70:71], v[42:43], v[54:55] op_sel:[0,1] op_sel_hi:[1,1]
	v_add_f32_e32 v72, v56, v57
	v_add_f32_e32 v73, v58, v59
	v_pk_fma_f32 v[0:1], v[0:1], v[32:33], v[64:65]
	v_add_f32_dpp v72, v72, v72 quad_perm:[1,0,3,2] row_mask:0xf bank_mask:0xf bound_ctrl:1
	v_add_f32_dpp v73, v73, v73 quad_perm:[1,0,3,2] row_mask:0xf bank_mask:0xf bound_ctrl:1
	v_pk_fma_f32 v[4:5], v[4:5], v[32:33], v[68:69]
	v_add_f32_dpp v72, v72, v72 quad_perm:[2,3,0,1] row_mask:0xf bank_mask:0xf bound_ctrl:1
	v_add_f32_dpp v73, v73, v73 quad_perm:[2,3,0,1] row_mask:0xf bank_mask:0xf bound_ctrl:1
	v_pk_fma_f32 v[2:3], v[2:3], v[34:35], v[66:67]
	v_add_f32_dpp v72, v72, v72 row_half_mirror row_mask:0xf bank_mask:0xf bound_ctrl:1
	v_add_f32_dpp v73, v73, v73 row_half_mirror row_mask:0xf bank_mask:0xf bound_ctrl:1
	v_pk_fma_f32 v[6:7], v[6:7], v[34:35], v[70:71]
	v_add_f32_dpp v74, v72, v72 row_mirror row_mask:0xf bank_mask:0xf bound_ctrl:1
	v_add_f32_dpp v76, v73, v73 row_mirror row_mask:0xf bank_mask:0xf bound_ctrl:1
	v_pk_fma_f32 v[0:1], v[36:37], v[74:75], v[0:1] op_sel_hi:[1,0,1]
	v_pk_fma_f32 v[2:3], v[38:39], v[74:75], v[2:3] op_sel_hi:[1,0,1]
	v_pk_fma_f32 v[4:5], v[36:37], v[76:77], v[4:5] op_sel_hi:[1,0,1]
	v_pk_fma_f32 v[6:7], v[38:39], v[76:77], v[6:7] op_sel_hi:[1,0,1]
	v_pk_mul_f32 v[60:61], v[0:1], v[44:45]
	v_pk_mul_f32 v[62:63], v[4:5], v[44:45]
	v_pk_fma_f32 v[60:61], v[2:3], v[46:47], v[60:61]
	v_pk_fma_f32 v[62:63], v[6:7], v[46:47], v[62:63]
	v_add_f32_e32 v105, v60, v61
	v_add_f32_e32 v121, v62, v63
	s_waitcnt lgkmcnt(0)
	ds_read_b128 v[28:31], v78 offset:38400
	ds_read_b128 v[32:35], v78 offset:38656
	ds_read_b128 v[36:39], v78 offset:38912
	ds_read_b128 v[40:43], v78 offset:39168
	ds_read_b128 v[44:47], v78 offset:39424
	v_pk_mul_f32 v[56:57], v[0:1], v[8:9]
	v_pk_mul_f32 v[58:59], v[4:5], v[8:9]
	v_pk_mul_f32 v[64:65], v[20:21], v[48:49] op_sel_hi:[1,0]
	v_pk_mul_f32 v[68:69], v[20:21], v[52:53] op_sel_hi:[1,0]
	v_pk_fma_f32 v[56:57], v[2:3], v[10:11], v[56:57]
	v_pk_fma_f32 v[58:59], v[6:7], v[10:11], v[58:59]
	v_pk_mul_f32 v[66:67], v[22:23], v[48:49] op_sel_hi:[1,0]
	v_pk_mul_f32 v[70:71], v[22:23], v[52:53] op_sel_hi:[1,0]
	v_add_f32_e32 v72, v56, v57
	v_add_f32_e32 v73, v58, v59
	v_pk_fma_f32 v[0:1], v[0:1], v[12:13], v[64:65]
	v_add_f32_dpp v72, v72, v72 quad_perm:[1,0,3,2] row_mask:0xf bank_mask:0xf bound_ctrl:1
	v_add_f32_dpp v73, v73, v73 quad_perm:[1,0,3,2] row_mask:0xf bank_mask:0xf bound_ctrl:1
	v_pk_fma_f32 v[4:5], v[4:5], v[12:13], v[68:69]
	v_add_f32_dpp v72, v72, v72 quad_perm:[2,3,0,1] row_mask:0xf bank_mask:0xf bound_ctrl:1
	v_add_f32_dpp v73, v73, v73 quad_perm:[2,3,0,1] row_mask:0xf bank_mask:0xf bound_ctrl:1
	v_pk_fma_f32 v[2:3], v[2:3], v[14:15], v[66:67]
	v_add_f32_dpp v72, v72, v72 row_half_mirror row_mask:0xf bank_mask:0xf bound_ctrl:1
	v_add_f32_dpp v73, v73, v73 row_half_mirror row_mask:0xf bank_mask:0xf bound_ctrl:1
	v_pk_fma_f32 v[6:7], v[6:7], v[14:15], v[70:71]
	v_add_f32_dpp v74, v72, v72 row_mirror row_mask:0xf bank_mask:0xf bound_ctrl:1
	v_add_f32_dpp v76, v73, v73 row_mirror row_mask:0xf bank_mask:0xf bound_ctrl:1
	v_pk_fma_f32 v[0:1], v[16:17], v[74:75], v[0:1] op_sel_hi:[1,0,1]
	v_pk_fma_f32 v[2:3], v[18:19], v[74:75], v[2:3] op_sel_hi:[1,0,1]
	v_pk_fma_f32 v[4:5], v[16:17], v[76:77], v[4:5] op_sel_hi:[1,0,1]
	v_pk_fma_f32 v[6:7], v[18:19], v[76:77], v[6:7] op_sel_hi:[1,0,1]
	v_pk_mul_f32 v[60:61], v[0:1], v[24:25]
	v_pk_mul_f32 v[62:63], v[4:5], v[24:25]
	v_pk_fma_f32 v[60:61], v[2:3], v[26:27], v[60:61]
	v_pk_fma_f32 v[62:63], v[6:7], v[26:27], v[62:63]
	v_add_f32_e32 v106, v60, v61
	v_add_f32_e32 v122, v62, v63
	s_waitcnt lgkmcnt(0)
	ds_read_b128 v[8:11], v78 offset:39936
	ds_read_b128 v[12:15], v78 offset:40192
	ds_read_b128 v[16:19], v78 offset:40448
	ds_read_b128 v[20:23], v78 offset:40704
	ds_read_b128 v[24:27], v78 offset:40960
	ds_read2st64_b32 v[50:51], v79 offset0:161 offset1:167
	ds_read2st64_b32 v[54:55], v81 offset0:161 offset1:167
	v_pk_mul_f32 v[56:57], v[0:1], v[28:29]
	v_pk_mul_f32 v[58:59], v[4:5], v[28:29]
	v_pk_mul_f32 v[64:65], v[40:41], v[48:49] op_sel:[0,1] op_sel_hi:[1,1]
	v_pk_mul_f32 v[68:69], v[40:41], v[52:53] op_sel:[0,1] op_sel_hi:[1,1]
	v_pk_fma_f32 v[56:57], v[2:3], v[30:31], v[56:57]
	v_pk_fma_f32 v[58:59], v[6:7], v[30:31], v[58:59]
	v_pk_mul_f32 v[66:67], v[42:43], v[48:49] op_sel:[0,1] op_sel_hi:[1,1]
	v_pk_mul_f32 v[70:71], v[42:43], v[52:53] op_sel:[0,1] op_sel_hi:[1,1]
	v_add_f32_e32 v72, v56, v57
	v_add_f32_e32 v73, v58, v59
	v_pk_fma_f32 v[0:1], v[0:1], v[32:33], v[64:65]
	v_add_f32_dpp v72, v72, v72 quad_perm:[1,0,3,2] row_mask:0xf bank_mask:0xf bound_ctrl:1
	v_add_f32_dpp v73, v73, v73 quad_perm:[1,0,3,2] row_mask:0xf bank_mask:0xf bound_ctrl:1
	v_pk_fma_f32 v[4:5], v[4:5], v[32:33], v[68:69]
	v_add_f32_dpp v72, v72, v72 quad_perm:[2,3,0,1] row_mask:0xf bank_mask:0xf bound_ctrl:1
	v_add_f32_dpp v73, v73, v73 quad_perm:[2,3,0,1] row_mask:0xf bank_mask:0xf bound_ctrl:1
	v_pk_fma_f32 v[2:3], v[2:3], v[34:35], v[66:67]
	v_add_f32_dpp v72, v72, v72 row_half_mirror row_mask:0xf bank_mask:0xf bound_ctrl:1
	v_add_f32_dpp v73, v73, v73 row_half_mirror row_mask:0xf bank_mask:0xf bound_ctrl:1
	v_pk_fma_f32 v[6:7], v[6:7], v[34:35], v[70:71]
	v_add_f32_dpp v74, v72, v72 row_mirror row_mask:0xf bank_mask:0xf bound_ctrl:1
	v_add_f32_dpp v76, v73, v73 row_mirror row_mask:0xf bank_mask:0xf bound_ctrl:1
	v_pk_fma_f32 v[0:1], v[36:37], v[74:75], v[0:1] op_sel_hi:[1,0,1]
	v_pk_fma_f32 v[2:3], v[38:39], v[74:75], v[2:3] op_sel_hi:[1,0,1]
	v_pk_fma_f32 v[4:5], v[36:37], v[76:77], v[4:5] op_sel_hi:[1,0,1]
	v_pk_fma_f32 v[6:7], v[38:39], v[76:77], v[6:7] op_sel_hi:[1,0,1]
	v_pk_mul_f32 v[60:61], v[0:1], v[44:45]
	v_pk_mul_f32 v[62:63], v[4:5], v[44:45]
	v_pk_fma_f32 v[60:61], v[2:3], v[46:47], v[60:61]
	v_pk_fma_f32 v[62:63], v[6:7], v[46:47], v[62:63]
	v_add_f32_e32 v107, v60, v61
	v_add_f32_e32 v123, v62, v63
	s_waitcnt lgkmcnt(0)
; DEV void scan_tile(const Params& p, int l, int tile, char* smem) {
;     ...
;       auto ldops = [&](ScanOps& o, int sl) {
;         const f32x4* b4 = (const f32x4*)(cb + sl * 384);
;         o.nkk0 = b4[cg * 2]; o.nkk1 = b4[cg * 2 + 1];
;         o.w0 = b4[16 + cg * 2]; o.w1 = b4[16 + cg * 2 + 1];
;         o.kka0 = b4[32 + cg * 2]; o.kka1 = b4[32 + cg * 2 + 1];
;         o.kd0 = b4[48 + cg * 2]; o.kd1 = b4[48 + cg * 2 + 1];
;         o.r0 = b4[64 + cg * 2]; o.r1 = b4[64 + cg * 2 + 1];
;         o.v = cb[sl * 384 + vo];
;       };
;       float ykeep = 0.f;
;       auto step = [&](const ScanOps& o, int sl) {
;         const f32x4 sA = S0 * o.nkk0 + S1 * o.nkk1;
;         const float sa = red8((sA[0] + sA[1]) + (sA[2] + sA[3]));
;         S0 = S0 * o.w0 + (o.kka0 * sa + o.kd0 * o.v);
;         S1 = S1 * o.w1 + (o.kka1 * sa + o.kd1 * o.v);
;         const f32x4 yA = S0 * o.r0 + S1 * o.r1;
;         const float y = red8((yA[0] + yA[1]) + (yA[2] + yA[3]));
;         ykeep = (cg == (sl & 7)) ? y : ykeep;
;       };
	ds_read_b128 v[28:31], v78 offset:41472
	ds_read_b128 v[32:35], v78 offset:41728
	ds_read_b128 v[36:39], v78 offset:41984
	ds_read_b128 v[40:43], v78 offset:42240
	ds_read_b128 v[44:47], v78 offset:42496
	v_pk_mul_f32 v[56:57], v[0:1], v[8:9]
	v_pk_mul_f32 v[58:59], v[4:5], v[8:9]
	v_pk_mul_f32 v[64:65], v[20:21], v[50:51] op_sel_hi:[1,0]
	v_pk_mul_f32 v[68:69], v[20:21], v[54:55] op_sel_hi:[1,0]
	v_pk_fma_f32 v[56:57], v[2:3], v[10:11], v[56:57]
	v_pk_fma_f32 v[58:59], v[6:7], v[10:11], v[58:59]
	v_pk_mul_f32 v[66:67], v[22:23], v[50:51] op_sel_hi:[1,0]
	v_pk_mul_f32 v[70:71], v[22:23], v[54:55] op_sel_hi:[1,0]
	v_add_f32_e32 v72, v56, v57
	v_add_f32_e32 v73, v58, v59
	v_pk_fma_f32 v[0:1], v[0:1], v[12:13], v[64:65]
	v_add_f32_dpp v72, v72, v72 quad_perm:[1,0,3,2] row_mask:0xf bank_mask:0xf bound_ctrl:1
	v_add_f32_dpp v73, v73, v73 quad_perm:[1,0,3,2] row_mask:0xf bank_mask:0xf bound_ctrl:1
	v_pk_fma_f32 v[4:5], v[4:5], v[12:13], v[68:69]
	v_add_f32_dpp v72, v72, v72 quad_perm:[2,3,0,1] row_mask:0xf bank_mask:0xf bound_ctrl:1
	v_add_f32_dpp v73, v73, v73 quad_perm:[2,3,0,1] row_mask:0xf bank_mask:0xf bound_ctrl:1
	v_pk_fma_f32 v[2:3], v[2:3], v[14:15], v[66:67]
	v_add_f32_dpp v72, v72, v72 row_half_mirror row_mask:0xf bank_mask:0xf bound_ctrl:1
	v_add_f32_dpp v73, v73, v73 row_half_mirror row_mask:0xf bank_mask:0xf bound_ctrl:1
	v_pk_fma_f32 v[6:7], v[6:7], v[14:15], v[70:71]
	v_add_f32_dpp v74, v72, v72 row_mirror row_mask:0xf bank_mask:0xf bound_ctrl:1
	v_add_f32_dpp v76, v73, v73 row_mirror row_mask:0xf bank_mask:0xf bound_ctrl:1
	v_pk_fma_f32 v[0:1], v[16:17], v[74:75], v[0:1] op_sel_hi:[1,0,1]
	v_pk_fma_f32 v[2:3], v[18:19], v[74:75], v[2:3] op_sel_hi:[1,0,1]
	v_pk_fma_f32 v[4:5], v[16:17], v[76:77], v[4:5] op_sel_hi:[1,0,1]
	v_pk_fma_f32 v[6:7], v[18:19], v[76:77], v[6:7] op_sel_hi:[1,0,1]
	v_pk_mul_f32 v[60:61], v[0:1], v[24:25]
	v_pk_mul_f32 v[62:63], v[4:5], v[24:25]
	v_pk_fma_f32 v[60:61], v[2:3], v[26:27], v[60:61]
	v_pk_fma_f32 v[62:63], v[6:7], v[26:27], v[62:63]
	v_add_f32_e32 v108, v60, v61
	v_add_f32_e32 v124, v62, v63
	s_waitcnt lgkmcnt(0)
	ds_read_b128 v[8:11], v78 offset:43008
	ds_read_b128 v[12:15], v78 offset:43264
	ds_read_b128 v[16:19], v78 offset:43520
	ds_read_b128 v[20:23], v78 offset:43776
	ds_read_b128 v[24:27], v78 offset:44032
	ds_read2st64_b32 v[48:49], v79 offset0:173 offset1:179
	ds_read2st64_b32 v[52:53], v81 offset0:173 offset1:179
	v_pk_mul_f32 v[56:57], v[0:1], v[28:29]
	v_pk_mul_f32 v[58:59], v[4:5], v[28:29]
	v_pk_mul_f32 v[64:65], v[40:41], v[50:51] op_sel:[0,1] op_sel_hi:[1,1]
	v_pk_mul_f32 v[68:69], v[40:41], v[54:55] op_sel:[0,1] op_sel_hi:[1,1]
	v_pk_fma_f32 v[56:57], v[2:3], v[30:31], v[56:57]
	v_pk_fma_f32 v[58:59], v[6:7], v[30:31], v[58:59]
	v_pk_mul_f32 v[66:67], v[42:43], v[50:51] op_sel:[0,1] op_sel_hi:[1,1]
	v_pk_mul_f32 v[70:71], v[42:43], v[54:55] op_sel:[0,1] op_sel_hi:[1,1]
	v_add_f32_e32 v72, v56, v57
	v_add_f32_e32 v73, v58, v59
	v_pk_fma_f32 v[0:1], v[0:1], v[32:33], v[64:65]
	v_add_f32_dpp v72, v72, v72 quad_perm:[1,0,3,2] row_mask:0xf bank_mask:0xf bound_ctrl:1
	v_add_f32_dpp v73, v73, v73 quad_perm:[1,0,3,2] row_mask:0xf bank_mask:0xf bound_ctrl:1
	v_pk_fma_f32 v[4:5], v[4:5], v[32:33], v[68:69]
	v_add_f32_dpp v72, v72, v72 quad_perm:[2,3,0,1] row_mask:0xf bank_mask:0xf bound_ctrl:1
	v_add_f32_dpp v73, v73, v73 quad_perm:[2,3,0,1] row_mask:0xf bank_mask:0xf bound_ctrl:1
	v_pk_fma_f32 v[2:3], v[2:3], v[34:35], v[66:67]
	v_add_f32_dpp v72, v72, v72 row_half_mirror row_mask:0xf bank_mask:0xf bound_ctrl:1
	v_add_f32_dpp v73, v73, v73 row_half_mirror row_mask:0xf bank_mask:0xf bound_ctrl:1
	v_pk_fma_f32 v[6:7], v[6:7], v[34:35], v[70:71]
	v_add_f32_dpp v74, v72, v72 row_mirror row_mask:0xf bank_mask:0xf bound_ctrl:1
	v_add_f32_dpp v76, v73, v73 row_mirror row_mask:0xf bank_mask:0xf bound_ctrl:1
	v_pk_fma_f32 v[0:1], v[36:37], v[74:75], v[0:1] op_sel_hi:[1,0,1]
	v_pk_fma_f32 v[2:3], v[38:39], v[74:75], v[2:3] op_sel_hi:[1,0,1]
	v_pk_fma_f32 v[4:5], v[36:37], v[76:77], v[4:5] op_sel_hi:[1,0,1]
	v_pk_fma_f32 v[6:7], v[38:39], v[76:77], v[6:7] op_sel_hi:[1,0,1]
	v_pk_mul_f32 v[60:61], v[0:1], v[44:45]
	v_pk_mul_f32 v[62:63], v[4:5], v[44:45]
	v_pk_fma_f32 v[60:61], v[2:3], v[46:47], v[60:61]
	v_pk_fma_f32 v[62:63], v[6:7], v[46:47], v[62:63]
	v_add_f32_e32 v109, v60, v61
	v_add_f32_e32 v125, v62, v63
	s_waitcnt lgkmcnt(0)
	ds_read_b128 v[28:31], v78 offset:44544
	ds_read_b128 v[32:35], v78 offset:44800
	ds_read_b128 v[36:39], v78 offset:45056
	ds_read_b128 v[40:43], v78 offset:45312
	ds_read_b128 v[44:47], v78 offset:45568
	v_pk_mul_f32 v[56:57], v[0:1], v[8:9]
	v_pk_mul_f32 v[58:59], v[4:5], v[8:9]
	v_pk_mul_f32 v[64:65], v[20:21], v[48:49] op_sel_hi:[1,0]
	v_pk_mul_f32 v[68:69], v[20:21], v[52:53] op_sel_hi:[1,0]
	v_pk_fma_f32 v[56:57], v[2:3], v[10:11], v[56:57]
	v_pk_fma_f32 v[58:59], v[6:7], v[10:11], v[58:59]
	v_pk_mul_f32 v[66:67], v[22:23], v[48:49] op_sel_hi:[1,0]
	v_pk_mul_f32 v[70:71], v[22:23], v[52:53] op_sel_hi:[1,0]
	v_add_f32_e32 v72, v56, v57
	v_add_f32_e32 v73, v58, v59
	v_pk_fma_f32 v[0:1], v[0:1], v[12:13], v[64:65]
	v_add_f32_dpp v72, v72, v72 quad_perm:[1,0,3,2] row_mask:0xf bank_mask:0xf bound_ctrl:1
	v_add_f32_dpp v73, v73, v73 quad_perm:[1,0,3,2] row_mask:0xf bank_mask:0xf bound_ctrl:1
	v_pk_fma_f32 v[4:5], v[4:5], v[12:13], v[68:69]
	v_add_f32_dpp v72, v72, v72 quad_perm:[2,3,0,1] row_mask:0xf bank_mask:0xf bound_ctrl:1
	v_add_f32_dpp v73, v73, v73 quad_perm:[2,3,0,1] row_mask:0xf bank_mask:0xf bound_ctrl:1
	v_pk_fma_f32 v[2:3], v[2:3], v[14:15], v[66:67]
	v_add_f32_dpp v72, v72, v72 row_half_mirror row_mask:0xf bank_mask:0xf bound_ctrl:1
	v_add_f32_dpp v73, v73, v73 row_half_mirror row_mask:0xf bank_mask:0xf bound_ctrl:1
	v_pk_fma_f32 v[6:7], v[6:7], v[14:15], v[70:71]
	v_add_f32_dpp v74, v72, v72 row_mirror row_mask:0xf bank_mask:0xf bound_ctrl:1
	v_add_f32_dpp v76, v73, v73 row_mirror row_mask:0xf bank_mask:0xf bound_ctrl:1
	v_pk_fma_f32 v[0:1], v[16:17], v[74:75], v[0:1] op_sel_hi:[1,0,1]
	v_pk_fma_f32 v[2:3], v[18:19], v[74:75], v[2:3] op_sel_hi:[1,0,1]
	v_pk_fma_f32 v[4:5], v[16:17], v[76:77], v[4:5] op_sel_hi:[1,0,1]
	v_pk_fma_f32 v[6:7], v[18:19], v[76:77], v[6:7] op_sel_hi:[1,0,1]
	v_pk_mul_f32 v[60:61], v[0:1], v[24:25]
	v_pk_mul_f32 v[62:63], v[4:5], v[24:25]
	v_pk_fma_f32 v[60:61], v[2:3], v[26:27], v[60:61]
	v_pk_fma_f32 v[62:63], v[6:7], v[26:27], v[62:63]
	v_add_f32_e32 v110, v60, v61
	v_add_f32_e32 v126, v62, v63
	s_waitcnt lgkmcnt(0)
; DEV void scan_tile(const Params& p, int l, int tile, char* smem) {
;     ...
;       auto ldops = [&](ScanOps& o, int sl) {
;         const f32x4* b4 = (const f32x4*)(cb + sl * 384);
;         o.nkk0 = b4[cg * 2]; o.nkk1 = b4[cg * 2 + 1];
;         o.w0 = b4[16 + cg * 2]; o.w1 = b4[16 + cg * 2 + 1];
;         o.kka0 = b4[32 + cg * 2]; o.kka1 = b4[32 + cg * 2 + 1];
;         o.kd0 = b4[48 + cg * 2]; o.kd1 = b4[48 + cg * 2 + 1];
;         o.r0 = b4[64 + cg * 2]; o.r1 = b4[64 + cg * 2 + 1];
;         o.v = cb[sl * 384 + vo];
;       };
;       float ykeep = 0.f;
;       auto step = [&](const ScanOps& o, int sl) {
;         const f32x4 sA = S0 * o.nkk0 + S1 * o.nkk1;
;         const float sa = red8((sA[0] + sA[1]) + (sA[2] + sA[3]));
;         S0 = S0 * o.w0 + (o.kka0 * sa + o.kd0 * o.v);
;         S1 = S1 * o.w1 + (o.kka1 * sa + o.kd1 * o.v);
;         const f32x4 yA = S0 * o.r0 + S1 * o.r1;
;         const float y = red8((yA[0] + yA[1]) + (yA[2] + yA[3]));
;         ykeep = (cg == (sl & 7)) ? y : ykeep;
;       };
	ds_read_b128 v[8:11], v78 offset:46080
	ds_read_b128 v[12:15], v78 offset:46336
	ds_read_b128 v[16:19], v78 offset:46592
	ds_read_b128 v[20:23], v78 offset:46848
	ds_read_b128 v[24:27], v78 offset:47104
	ds_read2st64_b32 v[50:51], v79 offset0:185 offset1:191
	ds_read2st64_b32 v[54:55], v81 offset0:185 offset1:191
	v_pk_mul_f32 v[56:57], v[0:1], v[28:29]
	v_pk_mul_f32 v[58:59], v[4:5], v[28:29]
	v_pk_mul_f32 v[64:65], v[40:41], v[48:49] op_sel:[0,1] op_sel_hi:[1,1]
	v_pk_mul_f32 v[68:69], v[40:41], v[52:53] op_sel:[0,1] op_sel_hi:[1,1]
	v_pk_fma_f32 v[56:57], v[2:3], v[30:31], v[56:57]
	v_pk_fma_f32 v[58:59], v[6:7], v[30:31], v[58:59]
	v_pk_mul_f32 v[66:67], v[42:43], v[48:49] op_sel:[0,1] op_sel_hi:[1,1]
	v_pk_mul_f32 v[70:71], v[42:43], v[52:53] op_sel:[0,1] op_sel_hi:[1,1]
	v_add_f32_e32 v72, v56, v57
	v_add_f32_e32 v73, v58, v59
	v_pk_fma_f32 v[0:1], v[0:1], v[32:33], v[64:65]
	v_add_f32_dpp v72, v72, v72 quad_perm:[1,0,3,2] row_mask:0xf bank_mask:0xf bound_ctrl:1
	v_add_f32_dpp v73, v73, v73 quad_perm:[1,0,3,2] row_mask:0xf bank_mask:0xf bound_ctrl:1
	v_pk_fma_f32 v[4:5], v[4:5], v[32:33], v[68:69]
	v_add_f32_dpp v72, v72, v72 quad_perm:[2,3,0,1] row_mask:0xf bank_mask:0xf bound_ctrl:1
	v_add_f32_dpp v73, v73, v73 quad_perm:[2,3,0,1] row_mask:0xf bank_mask:0xf bound_ctrl:1
	v_pk_fma_f32 v[2:3], v[2:3], v[34:35], v[66:67]
	v_add_f32_dpp v72, v72, v72 row_half_mirror row_mask:0xf bank_mask:0xf bound_ctrl:1
	v_add_f32_dpp v73, v73, v73 row_half_mirror row_mask:0xf bank_mask:0xf bound_ctrl:1
	v_pk_fma_f32 v[6:7], v[6:7], v[34:35], v[70:71]
	v_add_f32_dpp v74, v72, v72 row_mirror row_mask:0xf bank_mask:0xf bound_ctrl:1
	v_add_f32_dpp v76, v73, v73 row_mirror row_mask:0xf bank_mask:0xf bound_ctrl:1
	v_pk_fma_f32 v[0:1], v[36:37], v[74:75], v[0:1] op_sel_hi:[1,0,1]
	v_pk_fma_f32 v[2:3], v[38:39], v[74:75], v[2:3] op_sel_hi:[1,0,1]
	v_pk_fma_f32 v[4:5], v[36:37], v[76:77], v[4:5] op_sel_hi:[1,0,1]
	v_pk_fma_f32 v[6:7], v[38:39], v[76:77], v[6:7] op_sel_hi:[1,0,1]
	v_pk_mul_f32 v[60:61], v[0:1], v[44:45]
	v_pk_mul_f32 v[62:63], v[4:5], v[44:45]
	v_pk_fma_f32 v[60:61], v[2:3], v[46:47], v[60:61]
	v_pk_fma_f32 v[62:63], v[6:7], v[46:47], v[62:63]
	v_add_f32_e32 v111, v60, v61
	v_add_f32_e32 v127, v62, v63
	s_waitcnt lgkmcnt(0)
	ds_read_b128 v[28:31], v78 offset:47616
	ds_read_b128 v[32:35], v78 offset:47872
	ds_read_b128 v[36:39], v78 offset:48128
	ds_read_b128 v[40:43], v78 offset:48384
	ds_read_b128 v[44:47], v78 offset:48640
	v_pk_mul_f32 v[56:57], v[0:1], v[8:9]
	v_pk_mul_f32 v[58:59], v[4:5], v[8:9]
	v_pk_mul_f32 v[64:65], v[20:21], v[50:51] op_sel_hi:[1,0]
	v_pk_mul_f32 v[68:69], v[20:21], v[54:55] op_sel_hi:[1,0]
	v_pk_fma_f32 v[56:57], v[2:3], v[10:11], v[56:57]
	v_pk_fma_f32 v[58:59], v[6:7], v[10:11], v[58:59]
	v_pk_mul_f32 v[66:67], v[22:23], v[50:51] op_sel_hi:[1,0]
	v_pk_mul_f32 v[70:71], v[22:23], v[54:55] op_sel_hi:[1,0]
	v_add_f32_e32 v72, v56, v57
	v_add_f32_e32 v73, v58, v59
	v_pk_fma_f32 v[0:1], v[0:1], v[12:13], v[64:65]
	v_add_f32_dpp v72, v72, v72 quad_perm:[1,0,3,2] row_mask:0xf bank_mask:0xf bound_ctrl:1
	v_add_f32_dpp v73, v73, v73 quad_perm:[1,0,3,2] row_mask:0xf bank_mask:0xf bound_ctrl:1
	v_pk_fma_f32 v[4:5], v[4:5], v[12:13], v[68:69]
	v_add_f32_dpp v72, v72, v72 quad_perm:[2,3,0,1] row_mask:0xf bank_mask:0xf bound_ctrl:1
	v_add_f32_dpp v73, v73, v73 quad_perm:[2,3,0,1] row_mask:0xf bank_mask:0xf bound_ctrl:1
	v_pk_fma_f32 v[2:3], v[2:3], v[14:15], v[66:67]
	v_add_f32_dpp v72, v72, v72 row_half_mirror row_mask:0xf bank_mask:0xf bound_ctrl:1
	v_add_f32_dpp v73, v73, v73 row_half_mirror row_mask:0xf bank_mask:0xf bound_ctrl:1
	v_pk_fma_f32 v[6:7], v[6:7], v[14:15], v[70:71]
	v_add_f32_dpp v74, v72, v72 row_mirror row_mask:0xf bank_mask:0xf bound_ctrl:1
	v_add_f32_dpp v76, v73, v73 row_mirror row_mask:0xf bank_mask:0xf bound_ctrl:1
	v_pk_fma_f32 v[0:1], v[16:17], v[74:75], v[0:1] op_sel_hi:[1,0,1]
	v_pk_fma_f32 v[2:3], v[18:19], v[74:75], v[2:3] op_sel_hi:[1,0,1]
	v_pk_fma_f32 v[4:5], v[16:17], v[76:77], v[4:5] op_sel_hi:[1,0,1]
	v_pk_fma_f32 v[6:7], v[18:19], v[76:77], v[6:7] op_sel_hi:[1,0,1]
	v_pk_mul_f32 v[60:61], v[0:1], v[24:25]
	v_pk_mul_f32 v[62:63], v[4:5], v[24:25]
	v_pk_fma_f32 v[60:61], v[2:3], v[26:27], v[60:61]
	v_pk_fma_f32 v[62:63], v[6:7], v[26:27], v[62:63]
	v_add_f32_e32 v112, v60, v61
	v_add_f32_e32 v94, v62, v63
	s_waitcnt lgkmcnt(0)
; DEV void scan_tile(const Params& p, int l, int tile, char* smem) {
;     ...
;       auto step = [&](const ScanOps& o, int sl) {
;         const f32x4 sA = S0 * o.nkk0 + S1 * o.nkk1;
;         const float sa = red8((sA[0] + sA[1]) + (sA[2] + sA[3]));
;         S0 = S0 * o.w0 + (o.kka0 * sa + o.kd0 * o.v);
;         S1 = S1 * o.w1 + (o.kka1 * sa + o.kd1 * o.v);
;         const f32x4 yA = S0 * o.r0 + S1 * o.r1;
;         const float y = red8((yA[0] + yA[1]) + (yA[2] + yA[3]));
;         ykeep = (cg == (sl & 7)) ? y : ykeep;
;       };
;       ScanOps oa, ob;
;       ldops(oa, 0);
; #pragma unroll
;       for (int s8 = 0; s8 < 32; s8 += 8) {
; #pragma unroll
;         for (int q = 0; q < 8; q += 2) {
;           ldops(ob, s8 + q + 1);
;           step(oa, s8 + q);
;           ldops(oa, (s8 + q + 2) & 31);
;           step(ob, s8 + q + 1);
;         }
;         yw[s8 * 32] = ykeep;
	v_pk_mul_f32 v[56:57], v[0:1], v[28:29]
	v_pk_mul_f32 v[58:59], v[4:5], v[28:29]
	v_pk_mul_f32 v[64:65], v[40:41], v[50:51] op_sel:[0,1] op_sel_hi:[1,1]
	v_pk_mul_f32 v[68:69], v[40:41], v[54:55] op_sel:[0,1] op_sel_hi:[1,1]
	v_pk_fma_f32 v[56:57], v[2:3], v[30:31], v[56:57]
	v_pk_fma_f32 v[58:59], v[6:7], v[30:31], v[58:59]
	v_pk_mul_f32 v[66:67], v[42:43], v[50:51] op_sel:[0,1] op_sel_hi:[1,1]
	v_pk_mul_f32 v[70:71], v[42:43], v[54:55] op_sel:[0,1] op_sel_hi:[1,1]
	v_add_f32_e32 v72, v56, v57
	v_add_f32_e32 v73, v58, v59
	v_pk_fma_f32 v[0:1], v[0:1], v[32:33], v[64:65]
	v_add_f32_dpp v72, v72, v72 quad_perm:[1,0,3,2] row_mask:0xf bank_mask:0xf bound_ctrl:1
	v_add_f32_dpp v73, v73, v73 quad_perm:[1,0,3,2] row_mask:0xf bank_mask:0xf bound_ctrl:1
	v_pk_fma_f32 v[4:5], v[4:5], v[32:33], v[68:69]
	v_add_f32_dpp v72, v72, v72 quad_perm:[2,3,0,1] row_mask:0xf bank_mask:0xf bound_ctrl:1
	v_add_f32_dpp v73, v73, v73 quad_perm:[2,3,0,1] row_mask:0xf bank_mask:0xf bound_ctrl:1
	v_pk_fma_f32 v[2:3], v[2:3], v[34:35], v[66:67]
	v_add_f32_dpp v72, v72, v72 row_half_mirror row_mask:0xf bank_mask:0xf bound_ctrl:1
	v_add_f32_dpp v73, v73, v73 row_half_mirror row_mask:0xf bank_mask:0xf bound_ctrl:1
	v_pk_fma_f32 v[6:7], v[6:7], v[34:35], v[70:71]
	v_add_f32_dpp v74, v72, v72 row_mirror row_mask:0xf bank_mask:0xf bound_ctrl:1
	v_add_f32_dpp v76, v73, v73 row_mirror row_mask:0xf bank_mask:0xf bound_ctrl:1
	v_pk_fma_f32 v[0:1], v[36:37], v[74:75], v[0:1] op_sel_hi:[1,0,1]
	v_pk_fma_f32 v[2:3], v[38:39], v[74:75], v[2:3] op_sel_hi:[1,0,1]
	v_pk_fma_f32 v[4:5], v[36:37], v[76:77], v[4:5] op_sel_hi:[1,0,1]
	v_pk_fma_f32 v[6:7], v[38:39], v[76:77], v[6:7] op_sel_hi:[1,0,1]
	v_pk_mul_f32 v[60:61], v[0:1], v[44:45]
	v_pk_mul_f32 v[62:63], v[4:5], v[44:45]
	v_pk_fma_f32 v[60:61], v[2:3], v[46:47], v[60:61]
	v_pk_fma_f32 v[62:63], v[6:7], v[46:47], v[62:63]
	v_add_f32_e32 v113, v60, v61
	v_add_f32_e32 v95, v62, v63
	v_add_f32_dpp v98, v98, v98 row_mirror row_mask:0xf bank_mask:0x3 bound_ctrl:1
	v_add_f32_dpp v98, v106, v106 row_mirror row_mask:0xf bank_mask:0xc bound_ctrl:1
	v_add_f32_dpp v99, v99, v99 row_mirror row_mask:0xf bank_mask:0x3 bound_ctrl:1
	v_add_f32_dpp v99, v107, v107 row_mirror row_mask:0xf bank_mask:0xc bound_ctrl:1
	v_add_f32_dpp v100, v100, v100 row_mirror row_mask:0xf bank_mask:0x3 bound_ctrl:1
	v_add_f32_dpp v100, v108, v108 row_mirror row_mask:0xf bank_mask:0xc bound_ctrl:1
	v_add_f32_dpp v101, v101, v101 row_mirror row_mask:0xf bank_mask:0x3 bound_ctrl:1
	v_add_f32_dpp v101, v109, v109 row_mirror row_mask:0xf bank_mask:0xc bound_ctrl:1
	v_add_f32_dpp v102, v102, v102 row_mirror row_mask:0xf bank_mask:0x3 bound_ctrl:1
	v_add_f32_dpp v102, v110, v110 row_mirror row_mask:0xf bank_mask:0xc bound_ctrl:1
	v_add_f32_dpp v103, v103, v103 row_mirror row_mask:0xf bank_mask:0x3 bound_ctrl:1
	v_add_f32_dpp v103, v111, v111 row_mirror row_mask:0xf bank_mask:0xc bound_ctrl:1
	v_add_f32_dpp v104, v104, v104 row_mirror row_mask:0xf bank_mask:0x3 bound_ctrl:1
	v_add_f32_dpp v104, v112, v112 row_mirror row_mask:0xf bank_mask:0xc bound_ctrl:1
	v_add_f32_dpp v105, v105, v105 row_mirror row_mask:0xf bank_mask:0x3 bound_ctrl:1
	v_add_f32_dpp v105, v113, v113 row_mirror row_mask:0xf bank_mask:0xc bound_ctrl:1
	v_add_f32_dpp v98, v98, v98 row_half_mirror row_mask:0xf bank_mask:0x5 bound_ctrl:1
	v_add_f32_dpp v98, v102, v102 row_half_mirror row_mask:0xf bank_mask:0xa bound_ctrl:1
	v_add_f32_dpp v99, v99, v99 row_half_mirror row_mask:0xf bank_mask:0x5 bound_ctrl:1
	v_add_f32_dpp v99, v103, v103 row_half_mirror row_mask:0xf bank_mask:0xa bound_ctrl:1
	v_add_f32_dpp v100, v100, v100 row_half_mirror row_mask:0xf bank_mask:0x5 bound_ctrl:1
	v_add_f32_dpp v100, v104, v104 row_half_mirror row_mask:0xf bank_mask:0xa bound_ctrl:1
	v_add_f32_dpp v101, v101, v101 row_half_mirror row_mask:0xf bank_mask:0x5 bound_ctrl:1
; DEV void scan_tile(const Params& p, int l, int tile, char* smem) {
;     ...
;         const float y = red8((yA[0] + yA[1]) + (yA[2] + yA[3]));
;         ykeep = (cg == (sl & 7)) ? y : ykeep;
;       };
;       ScanOps oa, ob;
;       ldops(oa, 0);
; #pragma unroll
;       for (int s8 = 0; s8 < 32; s8 += 8) {
; #pragma unroll
;         for (int q = 0; q < 8; q += 2) {
;           ldops(ob, s8 + q + 1);
;           step(oa, s8 + q);
;           ldops(oa, (s8 + q + 2) & 31);
;           step(ob, s8 + q + 1);
;         }
;         yw[s8 * 32] = ykeep;
;       }
;     } else {
;       const int pw = w - 4;
;       if (ch > 0) flush(ch - 1, buf ^ 1, tid - 256);
;       if (ch + 1 < 136) produce(ch + 1, buf ^ 1, pw, 4);
;     }
;     __syncthreads();
;   }
	v_add_f32_dpp v101, v105, v105 row_half_mirror row_mask:0xf bank_mask:0xa bound_ctrl:1
	v_add_f32_dpp v98, v98, v98 quad_perm:[2,3,0,1] row_mask:0xf bank_mask:0xf bound_ctrl:1
	v_add_f32_dpp v99, v99, v99 quad_perm:[2,3,0,1] row_mask:0xf bank_mask:0xf bound_ctrl:1
	v_add_f32_dpp v100, v100, v100 quad_perm:[2,3,0,1] row_mask:0xf bank_mask:0xf bound_ctrl:1
	v_add_f32_dpp v101, v101, v101 quad_perm:[2,3,0,1] row_mask:0xf bank_mask:0xf bound_ctrl:1
	v_cndmask_b32_e64 v102, v100, v98, s[62:63]
	v_cndmask_b32_e64 v103, v101, v99, s[62:63]
	s_nop 0
	v_add_f32_dpp v102, v102, v102 quad_perm:[1,0,3,2] row_mask:0xf bank_mask:0xf bound_ctrl:1
	v_add_f32_dpp v103, v103, v103 quad_perm:[1,0,3,2] row_mask:0xf bank_mask:0xf bound_ctrl:1
	v_cndmask_b32_e64 v104, v103, v102, s[64:65]
	ds_write_b32 v80, v104 offset:2048
	v_add_f32_dpp v114, v114, v114 row_mirror row_mask:0xf bank_mask:0x3 bound_ctrl:1
	v_add_f32_dpp v114, v122, v122 row_mirror row_mask:0xf bank_mask:0xc bound_ctrl:1
	v_add_f32_dpp v115, v115, v115 row_mirror row_mask:0xf bank_mask:0x3 bound_ctrl:1
	v_add_f32_dpp v115, v123, v123 row_mirror row_mask:0xf bank_mask:0xc bound_ctrl:1
	v_add_f32_dpp v116, v116, v116 row_mirror row_mask:0xf bank_mask:0x3 bound_ctrl:1
	v_add_f32_dpp v116, v124, v124 row_mirror row_mask:0xf bank_mask:0xc bound_ctrl:1
	v_add_f32_dpp v117, v117, v117 row_mirror row_mask:0xf bank_mask:0x3 bound_ctrl:1
	v_add_f32_dpp v117, v125, v125 row_mirror row_mask:0xf bank_mask:0xc bound_ctrl:1
	v_add_f32_dpp v118, v118, v118 row_mirror row_mask:0xf bank_mask:0x3 bound_ctrl:1
	v_add_f32_dpp v118, v126, v126 row_mirror row_mask:0xf bank_mask:0xc bound_ctrl:1
	v_add_f32_dpp v119, v119, v119 row_mirror row_mask:0xf bank_mask:0x3 bound_ctrl:1
	v_add_f32_dpp v119, v127, v127 row_mirror row_mask:0xf bank_mask:0xc bound_ctrl:1
	v_add_f32_dpp v120, v120, v120 row_mirror row_mask:0xf bank_mask:0x3 bound_ctrl:1
	v_add_f32_dpp v120, v94, v94 row_mirror row_mask:0xf bank_mask:0xc bound_ctrl:1
	v_add_f32_dpp v121, v121, v121 row_mirror row_mask:0xf bank_mask:0x3 bound_ctrl:1
	v_add_f32_dpp v121, v95, v95 row_mirror row_mask:0xf bank_mask:0xc bound_ctrl:1
	v_add_f32_dpp v114, v114, v114 row_half_mirror row_mask:0xf bank_mask:0x5 bound_ctrl:1
	v_add_f32_dpp v114, v118, v118 row_half_mirror row_mask:0xf bank_mask:0xa bound_ctrl:1
	v_add_f32_dpp v115, v115, v115 row_half_mirror row_mask:0xf bank_mask:0x5 bound_ctrl:1
	v_add_f32_dpp v115, v119, v119 row_half_mirror row_mask:0xf bank_mask:0xa bound_ctrl:1
	v_add_f32_dpp v116, v116, v116 row_half_mirror row_mask:0xf bank_mask:0x5 bound_ctrl:1
	v_add_f32_dpp v116, v120, v120 row_half_mirror row_mask:0xf bank_mask:0xa bound_ctrl:1
	v_add_f32_dpp v117, v117, v117 row_half_mirror row_mask:0xf bank_mask:0x5 bound_ctrl:1
	v_add_f32_dpp v117, v121, v121 row_half_mirror row_mask:0xf bank_mask:0xa bound_ctrl:1
	v_add_f32_dpp v114, v114, v114 quad_perm:[2,3,0,1] row_mask:0xf bank_mask:0xf bound_ctrl:1
	v_add_f32_dpp v115, v115, v115 quad_perm:[2,3,0,1] row_mask:0xf bank_mask:0xf bound_ctrl:1
	v_add_f32_dpp v116, v116, v116 quad_perm:[2,3,0,1] row_mask:0xf bank_mask:0xf bound_ctrl:1
	v_add_f32_dpp v117, v117, v117 quad_perm:[2,3,0,1] row_mask:0xf bank_mask:0xf bound_ctrl:1
	v_cndmask_b32_e64 v118, v116, v114, s[62:63]
	v_cndmask_b32_e64 v119, v117, v115, s[62:63]
	s_nop 0
	v_add_f32_dpp v118, v118, v118 quad_perm:[1,0,3,2] row_mask:0xf bank_mask:0xf bound_ctrl:1
	v_add_f32_dpp v119, v119, v119 quad_perm:[1,0,3,2] row_mask:0xf bank_mask:0xf bound_ctrl:1
	v_cndmask_b32_e64 v120, v119, v118, s[64:65]
	ds_write_b32 v82, v120 offset:2048
	v_xor_b32_e32 v78, 0xc000, v78
	v_xor_b32_e32 v79, 0xc000, v79
	v_xor_b32_e32 v81, 0xc000, v81
	v_xor_b32_e32 v80, 0x1000, v80
	v_xor_b32_e32 v82, 0x1000, v82
	s_add_u32 s46, s46, 1
	s_cmp_lt_u32 s46, 136
	s_waitcnt lgkmcnt(0)
	s_barrier
	s_cbranch_scc1 .Lsc_cloop
	s_branch .LBB0_192
